# k21 with filt_pipe v2: all 16 w3 loads of the next filter block issued behind the current block's MFMAs (load s right after MFMA s), decay one block ahead
# speedup vs baseline: 1.0059x; 1.0059x over previous
; __device__ __forceinline__ void filt_item(const Params& p, int lsel, int tile, float* lds, int wave, float (&colsum)[16], bool flush) {
;     ...
;         const int lane = tid & 63, l15 = lane & 15, g = lane >> 4, wv = tid >> 6;
;         float av[16];
; #pragma unroll
;         for (int s_ = 0; s_ < 16; ++s_) av[s_] = h2[l15 * 64 + 4 * s_ + g];
;         const float inv_lm1 = 1.f / (float)(L - 1);
; #pragma unroll
;         for (int ct = 0; ct < 16; ++ct) {
;             const int col = wv * 256 + ct * 16 + l15;
;             const float* wp = p.hy_pos_w3 + (size_t)g * 2048 + col;
;             f32x4 acc = (f32x4){0.f, 0.f, 0.f, 0.f};
; #pragma unroll
;             for (int s_ = 0; s_ < 16; ++s_) acc = __builtin_amdgcn_mfma_f32_16x16x4f32(av[s_], wp[(size_t)s_ * 4 * 2048], acc, 0, 0, 0);
.LBB0_75:
	s_or_b64 exec, exec, s[8:9]
	s_and_b32 s0, 0xffff, s24
	s_cmp_lg_u32 s0, 0
	s_cselect_b64 s[0:1], -1, 0
	s_cmp_lg_u64 s[0:1], 0
	s_addc_u32 s4, s61, s93
	s_cmpk_gt_i32 s4, 0x47f
	s_cselect_b64 s[0:1], -1, 0
	s_cmpk_lt_i32 s4, 0x400
	s_cselect_b64 s[4:5], -1, 0
	s_xor_b64 s[4:5], s[30:31], s[4:5]
	s_or_b64 s[8:9], s[0:1], s[4:5]
	s_and_b64 s[0:1], s[30:31], exec
	s_mov_b32 s0, 0x29b00000
	v_readlane_b32 s4, v253, 8
	s_cselect_b32 s0, s0, 0x31b00000
	v_readlane_b32 s6, v253, 10
	v_readlane_b32 s5, v253, 9
	v_readlane_b32 s7, v253, 11
	s_add_u32 s4, s6, s0
	s_addc_u32 s5, s7, 0
	s_and_b64 s[0:1], s[30:31], exec
	s_cselect_b32 s0, 0x2000, 0
	s_add_u32 s6, s6, s0
	s_addc_u32 s7, s7, 0
	v_and_b32_e32 v10, 15, v14
	s_add_i32 s3, s3, -1
	s_movk_i32 s0, 0xff00
	v_and_or_b32 v2, v16, s0, v10
	s_and_b64 s[0:1], s[30:31], exec
	s_cselect_b32 s24, 14, 11
	s_ashr_i32 s29, s28, 31
	s_lshl_b64 s[0:1], s[28:29], 2
	v_bfe_u32 v30, v14, 4, 2
	s_add_u32 s0, s4, s0
	s_addc_u32 s1, s5, s1
	v_lshlrev_b32_e32 v0, 4, v30
	v_readlane_b32 s76, v253, 28
	v_lshl_add_u64 v[4:5], s[0:1], 0, v[0:1]
	v_lshlrev_b32_e32 v0, 13, v30
	v_readlane_b32 s90, v253, 42
	v_readlane_b32 s91, v253, 43
	v_ashrrev_i32_e32 v3, 31, v2
	v_lshlrev_b64 v[16:17], 2, v[2:3]
	v_lshl_add_u64 v[6:7], s[90:91], 0, v[0:1]
	v_lshl_add_u64 v[6:7], v[6:7], 0, v[16:17]
	s_mov_b32 s100, 0x8000
	s_mov_b32 s101, 0
	v_lshl_add_u64 v[204:205], v[6:7], 0, s[100:101]
	v_lshl_add_u64 v[206:207], v[204:205], 0, s[100:101]
	v_lshl_add_u64 v[208:209], v[206:207], 0, s[100:101]
	v_lshl_add_u64 v[210:211], v[208:209], 0, s[100:101]
	v_lshl_add_u64 v[212:213], v[210:211], 0, s[100:101]
	v_lshl_add_u64 v[214:215], v[212:213], 0, s[100:101]
	v_lshl_add_u64 v[216:217], v[214:215], 0, s[100:101]
	v_lshl_add_u64 v[218:219], v[216:217], 0, s[100:101]
	v_lshl_add_u64 v[220:221], v[218:219], 0, s[100:101]
	v_lshl_add_u64 v[222:223], v[220:221], 0, s[100:101]
	v_lshl_add_u64 v[224:225], v[222:223], 0, s[100:101]
	v_lshl_add_u64 v[226:227], v[224:225], 0, s[100:101]
	v_lshl_add_u64 v[228:229], v[226:227], 0, s[100:101]
	v_lshl_add_u64 v[230:231], v[228:229], 0, s[100:101]
	v_lshl_add_u64 v[232:233], v[230:231], 0, s[100:101]
	s_waitcnt lgkmcnt(0)
	s_barrier
	global_load_dword v0, v[6:7], off
	s_mov_b32 s0, 0x8000
	v_add_co_u32_e32 v8, vcc, s0, v6
	s_mov_b32 s0, 0x10000
	s_nop 0
	v_addc_co_u32_e32 v9, vcc, 0, v7, vcc
	global_load_dword v18, v[8:9], off
	v_add_co_u32_e32 v8, vcc, s0, v6
	s_mov_b32 s0, 0x18000
	s_nop 0
	v_addc_co_u32_e32 v9, vcc, 0, v7, vcc
	global_load_dword v22, v[8:9], off
	v_add_co_u32_e32 v8, vcc, s0, v6
	s_mov_b32 s0, 0x20000
	s_nop 0
	v_addc_co_u32_e32 v9, vcc, 0, v7, vcc
	global_load_dword v23, v[8:9], off
	v_add_co_u32_e32 v8, vcc, s0, v6
	s_mov_b32 s0, 0x28000
	s_nop 0
	v_addc_co_u32_e32 v9, vcc, 0, v7, vcc
	global_load_dword v26, v[8:9], off
	v_add_co_u32_e32 v8, vcc, s0, v6
	s_mov_b32 s1, 0x30000
	s_nop 0
	v_addc_co_u32_e32 v9, vcc, 0, v7, vcc
	global_load_dword v27, v[8:9], off
	v_add_co_u32_e32 v8, vcc, s1, v6
	v_lshlrev_b32_e32 v10, 8, v10
	s_nop 0
	v_addc_co_u32_e32 v9, vcc, 0, v7, vcc
	global_load_dword v28, v[8:9], off
	v_lshlrev_b32_e32 v31, 2, v30
	v_add3_u32 v8, 0, v10, v31
	v_add_u32_e32 v32, 0x1800, v8
	ds_read2_b32 v[14:15], v32 offset0:64 offset1:68
	s_mov_b32 s0, 0x38000
	v_add_co_u32_e32 v8, vcc, s0, v6
	s_mov_b32 s0, 0x40000
	s_nop 0
	v_addc_co_u32_e32 v9, vcc, 0, v7, vcc
	global_load_dword v29, v[8:9], off
	v_add_co_u32_e32 v12, vcc, s0, v6
	s_mov_b32 s0, 0x48000
	s_nop 0
	v_addc_co_u32_e32 v13, vcc, 0, v7, vcc
	v_add_co_u32_e32 v20, vcc, s0, v6
	s_mov_b32 s0, 0x50000
	s_nop 0
	v_addc_co_u32_e32 v21, vcc, 0, v7, vcc
	s_waitcnt lgkmcnt(0)
	s_waitcnt vmcnt(7)
	v_mfma_f32_16x16x4_f32 v[8:11], v14, v0, 0
	global_load_dword v234, v[6:7], off offset:64
	global_load_dword v0, v[12:13], off
	global_load_dword v33, v[20:21], off
	v_add_co_u32_e32 v20, vcc, s0, v6
	s_mov_b32 s0, 0x58000
	s_nop 0
	v_addc_co_u32_e32 v21, vcc, 0, v7, vcc
	s_waitcnt vmcnt(9)
	v_mfma_f32_16x16x4_f32 v[8:11], v15, v18, v[8:11]
	global_load_dword v235, v[204:205], off offset:64
	ds_read2_b32 v[18:19], v32 offset0:72 offset1:76
	global_load_dword v34, v[20:21], off
	v_add_co_u32_e32 v24, vcc, s0, v6
	s_mov_b32 s1, 0x60000
	s_nop 0
	v_addc_co_u32_e32 v25, vcc, 0, v7, vcc
	s_waitcnt lgkmcnt(0)
	s_waitcnt vmcnt(10)
	v_mfma_f32_16x16x4_f32 v[10:13], v18, v22, v[8:11]
	global_load_dword v236, v[206:207], off offset:64
	s_nop 1
	ds_read2_b32 v[8:9], v32 offset0:80 offset1:84
	global_load_dword v35, v[24:25], off
	s_mov_b32 s0, 0x68000
	v_readlane_b32 s77, v253, 29
	v_readlane_b32 s78, v253, 30
	v_readlane_b32 s79, v253, 31
	v_readlane_b32 s80, v253, 32
	s_waitcnt vmcnt(11)
	v_mfma_f32_16x16x4_f32 v[10:13], v19, v23, v[10:13]
	global_load_dword v237, v[208:209], off offset:64
	v_readlane_b32 s81, v253, 33
	v_readlane_b32 s82, v253, 34
	v_readlane_b32 s83, v253, 35
	v_readlane_b32 s84, v253, 36
	v_readlane_b32 s85, v253, 37
	v_readlane_b32 s86, v253, 38
	v_readlane_b32 s87, v253, 39
	s_waitcnt lgkmcnt(0)
	s_waitcnt vmcnt(11)
; __device__ __forceinline__ void filt_item(const Params& p, int lsel, int tile, float* lds, int wave, float (&colsum)[16], bool flush) {
;     ...
;         for (int ct = 0; ct < 16; ++ct) {
;             const int col = wv * 256 + ct * 16 + l15;
;             const float* wp = p.hy_pos_w3 + (size_t)g * 2048 + col;
;             f32x4 acc = (f32x4){0.f, 0.f, 0.f, 0.f};
; #pragma unroll
;             for (int s_ = 0; s_ < 16; ++s_) acc = __builtin_amdgcn_mfma_f32_16x16x4f32(av[s_], wp[(size_t)s_ * 4 * 2048], acc, 0, 0, 0);
;             const float dec = fabsf(p.hy_decay[col]); float asum = 0.f;
; #pragma unroll
;             for (int r = 0; r < 4; ++r) { const float tn = (float)(t0 + 4 * g + r) * inv_lm1; acc[r] *= __expf(-tn * dec); asum += fabsf(acc[r]); }
;             *(f32x4*)(filt + (size_t)col * L + t0 + 4 * g) = acc;
;             colsum[ct] += asum;
;             if (flush) { float tot = colsum[ct]; tot += __shfl_xor(tot, 16); tot += __shfl_xor(tot, 32); if (g == 0) atomicAdd(normsum + col, tot); colsum[ct] = 0.f; }
	v_mfma_f32_16x16x4_f32 v[20:23], v8, v26, v[10:13]
	global_load_dword v238, v[210:211], off offset:64
	s_nop 0
	v_add_co_u32_e32 v12, vcc, s1, v6
	s_mov_b32 s1, 0x70000
	s_nop 0
	v_addc_co_u32_e32 v13, vcc, 0, v7, vcc
	global_load_dword v36, v[12:13], off
	v_add_co_u32_e32 v24, vcc, s0, v6
	s_mov_b32 s0, 0x78000
	s_nop 0
	v_addc_co_u32_e32 v25, vcc, 0, v7, vcc
	global_load_dword v37, v[24:25], off
	v_add_co_u32_e32 v24, vcc, s1, v6
	v_readlane_b32 s88, v253, 40
	s_nop 0
	v_addc_co_u32_e32 v25, vcc, 0, v7, vcc
	global_load_dword v39, v[24:25], off
	v_readlane_b32 s89, v253, 41
	v_add_co_u32_e32 v26, vcc, s0, v6
	ds_read2_b32 v[10:11], v32 offset0:88 offset1:92
	s_waitcnt vmcnt(14)
	v_mfma_f32_16x16x4_f32 v[20:23], v9, v27, v[20:23]
	global_load_dword v239, v[212:213], off offset:64
	v_readlane_b32 s76, v253, 44
	v_addc_co_u32_e32 v27, vcc, 0, v7, vcc
	v_readlane_b32 s77, v253, 45
	global_load_dword v65, v[26:27], off
	ds_read2_b32 v[12:13], v32 offset0:96 offset1:100
	v_lshl_add_u64 v[16:17], s[76:77], 0, v[16:17]
	global_load_dword v38, v[16:17], off
	global_load_dword v251, v[16:17], off offset:64
	s_waitcnt lgkmcnt(1)
	s_waitcnt vmcnt(17)
	v_mfma_f32_16x16x4_f32 v[20:23], v10, v28, v[20:23]
	global_load_dword v240, v[214:215], off offset:64
	v_cvt_f32_u32_e32 v68, s3
	v_cmp_eq_u32_e64 s[0:1], 0, v30
	v_readlane_b32 s78, v253, 46
	v_readlane_b32 s79, v253, 47
	v_div_scale_f32 v70, s[4:5], v68, v68, 1.0
	v_rcp_f32_e32 v71, v70
	s_waitcnt vmcnt(17)
	v_mfma_f32_16x16x4_f32 v[20:23], v11, v29, v[20:23]
	global_load_dword v241, v[216:217], off offset:64
	v_div_scale_f32 v72, vcc, 1.0, v68, 1.0
	v_readlane_b32 s80, v253, 48
	v_readlane_b32 s81, v253, 49
	v_readlane_b32 s82, v253, 50
	v_readlane_b32 s83, v253, 51
	v_readlane_b32 s84, v253, 52
	s_waitcnt lgkmcnt(0)
	s_waitcnt vmcnt(16)
	v_mfma_f32_16x16x4_f32 v[22:25], v12, v0, v[20:23]
	global_load_dword v242, v[218:219], off offset:64
	s_nop 1
	ds_read2_b32 v[20:21], v32 offset0:104 offset1:108
	v_or_b32_e32 v0, s28, v31
	v_or_b32_e32 v30, 1, v0
	v_or_b32_e32 v31, 2, v0
	v_cvt_f32_i32_e32 v67, v30
	v_fma_f32 v30, -v70, v71, 1.0
	v_cvt_f32_i32_e32 v69, v31
	s_waitcnt vmcnt(16)
	v_mfma_f32_16x16x4_f32 v[26:29], v13, v33, v[22:25]
	global_load_dword v243, v[220:221], off offset:64
	ds_read2_b32 v[24:25], v32 offset0:112 offset1:116
	ds_read2_b32 v[22:23], v32 offset0:120 offset1:124
	v_fmac_f32_e32 v71, v30, v71
	v_mul_f32_e32 v73, v72, v71
	v_cvt_f32_i32_e32 v66, v0
	v_or_b32_e32 v0, 3, v0
	v_cvt_f32_i32_e32 v0, v0
	s_waitcnt lgkmcnt(2)
	s_waitcnt vmcnt(15)
	v_mfma_f32_16x16x4_f32 v[26:29], v20, v34, v[26:29]
	global_load_dword v244, v[222:223], off offset:64
	v_readlane_b32 s85, v253, 53
	v_readlane_b32 s86, v253, 54
	v_readlane_b32 s87, v253, 55
	v_readlane_b32 s88, v253, 56
	v_readlane_b32 s89, v253, 57
	v_readlane_b32 s90, v253, 58
	v_readlane_b32 s91, v253, 59
	s_waitcnt vmcnt(14)
	v_mfma_f32_16x16x4_f32 v[26:29], v21, v35, v[26:29]
	global_load_dword v245, v[224:225], off offset:64
	v_lshlrev_b64 v[34:35], s24, v[2:3]
	v_lshl_add_u64 v[34:35], v[34:35], 2, v[4:5]
	s_waitcnt lgkmcnt(1)
	s_waitcnt vmcnt(12)
	v_mfma_f32_16x16x4_f32 v[30:33], v24, v36, v[26:29]
	global_load_dword v246, v[226:227], off offset:64
	s_nop 5
	v_fma_f32 v26, -v70, v73, v72
	v_fmac_f32_e32 v73, v26, v71
	v_fma_f32 v26, -v70, v73, v72
	v_div_fmas_f32 v26, v26, v71, v73
	v_div_fixup_f32 v29, v26, v68, 1.0
	v_mul_f32_e64 v28, v29, -v66
	v_mul_f32_e64 v27, v29, -v67
	s_waitcnt vmcnt(12)
	v_mfma_f32_16x16x4_f32 v[30:33], v25, v37, v[30:33]
	global_load_dword v247, v[228:229], off offset:64
	v_mul_f32_e64 v26, v29, -v69
	v_mul_f32_e64 v0, v29, -v0
	s_and_b64 vcc, exec, s[8:9]
	s_waitcnt vmcnt(9)
	v_mul_f32_e64 v29, v28, |v38|
	s_waitcnt lgkmcnt(0)
	v_mfma_f32_16x16x4_f32 v[30:33], v22, v39, v[30:33]
	global_load_dword v248, v[230:231], off offset:64
	v_mul_f32_e64 v36, v27, |v38|
	v_mul_f32_e64 v37, v26, |v38|
	v_mul_f32_e64 v38, v0, |v38|
	v_mul_f32_e32 v29, 0x3fb8aa3b, v29
	v_mul_f32_e32 v39, 0x3fb8aa3b, v36
	v_mul_f32_e32 v66, 0x3fb8aa3b, v37
	v_mul_f32_e32 v67, 0x3fb8aa3b, v38
	v_mfma_f32_16x16x4_f32 v[30:33], v23, v65, v[30:33]
	global_load_dword v249, v[232:233], off offset:64
	v_exp_f32_e32 v36, v29
	v_exp_f32_e32 v37, v39
	v_exp_f32_e32 v38, v66
	v_exp_f32_e32 v39, v67
	s_nop 5
	v_pk_mul_f32 v[30:31], v[30:31], v[36:37]
	v_pk_mul_f32 v[32:33], v[32:33], v[38:39]
	v_add_f32_e64 v29, |v30|, |v31|
	v_add_f32_e64 v29, |v32|, v29
	v_add_f32_e64 v29, |v33|, v29
	v_add_f32_e32 v64, v64, v29
	global_store_dwordx4 v[34:35], v[30:33], off
	s_cbranch_vccz .LBB0_79
	s_nop 0
	v_and_b32_e32 v30, 64, v48
	v_xor_b32_e32 v29, 16, v48
	v_add_u32_e32 v30, 64, v30
	v_cmp_lt_i32_e32 vcc, v29, v30
	v_xor_b32_e32 v31, 32, v48
	s_nop 0
	v_cndmask_b32_e32 v29, v48, v29, vcc
	v_lshlrev_b32_e32 v29, 2, v29
	ds_bpermute_b32 v29, v29, v64
	v_cmp_lt_i32_e32 vcc, v31, v30
	s_waitcnt lgkmcnt(0)
	v_add_f32_e32 v29, v64, v29
	v_cndmask_b32_e32 v30, v48, v31, vcc
	v_lshlrev_b32_e32 v30, 2, v30
	ds_bpermute_b32 v30, v30, v29
	s_and_saveexec_b64 s[4:5], s[0:1]
	s_cbranch_execz .LBB0_78
	v_lshl_add_u64 v[32:33], v[2:3], 2, s[6:7]
	s_waitcnt lgkmcnt(0)
	v_add_f32_e32 v29, v29, v30
	global_atomic_add_f32 v[32:33], v29, off

; __device__ __forceinline__ void filt_item(const Params& p, int lsel, int tile, float* lds, int wave, float (&colsum)[16], bool flush) {
;     ...
;         for (int ct = 0; ct < 16; ++ct) {
;             const int col = wv * 256 + ct * 16 + l15;
;             const float* wp = p.hy_pos_w3 + (size_t)g * 2048 + col;
;             f32x4 acc = (f32x4){0.f, 0.f, 0.f, 0.f};
; #pragma unroll
;             for (int s_ = 0; s_ < 16; ++s_) acc = __builtin_amdgcn_mfma_f32_16x16x4f32(av[s_], wp[(size_t)s_ * 4 * 2048], acc, 0, 0, 0);
;             const float dec = fabsf(p.hy_decay[col]); float asum = 0.f;
; #pragma unroll
;             for (int r = 0; r < 4; ++r) { const float tn = (float)(t0 + 4 * g + r) * inv_lm1; acc[r] *= __expf(-tn * dec); asum += fabsf(acc[r]); }
;             *(f32x4*)(filt + (size_t)col * L + t0 + 4 * g) = acc;
;             colsum[ct] += asum;
;             if (flush) { float tot = colsum[ct]; tot += __shfl_xor(tot, 16); tot += __shfl_xor(tot, 32); if (g == 0) atomicAdd(normsum + col, tot); colsum[ct] = 0.f; }
.LBB0_79:
	s_waitcnt lgkmcnt(0)
	v_mfma_f32_16x16x4_f32 v[30:33], v14, v234, 0
	global_load_dword v234, v[6:7], off offset:128
	global_load_dword v250, v[16:17], off offset:128
	v_mfma_f32_16x16x4_f32 v[30:33], v15, v235, v[30:33]
	global_load_dword v235, v[204:205], off offset:128
	v_mfma_f32_16x16x4_f32 v[30:33], v18, v236, v[30:33]
	global_load_dword v236, v[206:207], off offset:128
	v_mfma_f32_16x16x4_f32 v[30:33], v19, v237, v[30:33]
	global_load_dword v237, v[208:209], off offset:128
	v_mfma_f32_16x16x4_f32 v[30:33], v8, v238, v[30:33]
	global_load_dword v238, v[210:211], off offset:128
	v_mfma_f32_16x16x4_f32 v[30:33], v9, v239, v[30:33]
	global_load_dword v239, v[212:213], off offset:128
	s_waitcnt vmcnt(17)
	v_mfma_f32_16x16x4_f32 v[30:33], v10, v240, v[30:33]
	global_load_dword v240, v[214:215], off offset:128
	s_waitcnt vmcnt(17)
	v_mfma_f32_16x16x4_f32 v[30:33], v11, v241, v[30:33]
	global_load_dword v241, v[216:217], off offset:128
	s_nop 0
	s_nop 0
	s_waitcnt vmcnt(17)
	v_mfma_f32_16x16x4_f32 v[30:33], v12, v242, v[30:33]
	global_load_dword v242, v[218:219], off offset:128
	v_or_b32_e32 v34, 16, v2
	v_ashrrev_i32_e32 v35, 31, v34
	v_lshlrev_b64 v[34:35], s24, v[34:35]
	v_lshl_add_u64 v[34:35], v[34:35], 2, v[4:5]
	s_andn2_b64 vcc, exec, s[8:9]
	v_mul_f32_e64 v39, v27, |v251|
	s_waitcnt vmcnt(17)
	v_mfma_f32_16x16x4_f32 v[30:33], v13, v243, v[30:33]
	global_load_dword v243, v[220:221], off offset:128
	v_mul_f32_e64 v65, v26, |v251|
	s_waitcnt vmcnt(17)
	v_mfma_f32_16x16x4_f32 v[30:33], v20, v244, v[30:33]
	global_load_dword v244, v[222:223], off offset:128
	s_waitcnt vmcnt(17)
	v_mfma_f32_16x16x4_f32 v[30:33], v21, v245, v[30:33]
	global_load_dword v245, v[224:225], off offset:128
	s_waitcnt vmcnt(17)
	v_mfma_f32_16x16x4_f32 v[30:33], v24, v246, v[30:33]
	global_load_dword v246, v[226:227], off offset:128
	s_waitcnt vmcnt(17)
	v_mfma_f32_16x16x4_f32 v[30:33], v25, v247, v[30:33]
	global_load_dword v247, v[228:229], off offset:128
	v_cndmask_b32_e64 v29, 0, 1, s[8:9]
	v_cmp_ne_u32_e64 s[4:5], 1, v29
	v_mul_f32_e64 v29, v28, |v251|
	v_mul_f32_e32 v29, 0x3fb8aa3b, v29
	s_waitcnt vmcnt(17)
	v_mfma_f32_16x16x4_f32 v[30:33], v22, v248, v[30:33]
	global_load_dword v248, v[230:231], off offset:128
	v_mul_f32_e64 v36, v0, |v251|
	v_mul_f32_e32 v37, 0x3fb8aa3b, v39
	v_mul_f32_e32 v39, 0x3fb8aa3b, v65
	v_mul_f32_e32 v65, 0x3fb8aa3b, v36
	v_exp_f32_e32 v36, v29
	v_exp_f32_e32 v37, v37
	s_waitcnt vmcnt(17)
	v_mfma_f32_16x16x4_f32 v[30:33], v23, v249, v[30:33]
	global_load_dword v249, v[232:233], off offset:128
	v_exp_f32_e32 v38, v39
	v_exp_f32_e32 v39, v65
	s_nop 7
	v_pk_mul_f32 v[30:31], v[30:31], v[36:37]
	v_pk_mul_f32 v[32:33], v[32:33], v[38:39]
	v_add_f32_e64 v29, |v30|, |v31|
	v_add_f32_e64 v29, |v32|, v29
	v_add_f32_e64 v29, |v33|, v29
	v_add_f32_e32 v63, v63, v29
	global_store_dwordx4 v[34:35], v[30:33], off
	s_cbranch_vccnz .LBB0_83
	s_nop 0
	v_and_b32_e32 v30, 64, v48
	v_xor_b32_e32 v29, 16, v48
	v_add_u32_e32 v30, 64, v30
	v_cmp_lt_i32_e32 vcc, v29, v30
	v_xor_b32_e32 v31, 32, v48
	s_nop 0
	v_cndmask_b32_e32 v29, v48, v29, vcc
	v_lshlrev_b32_e32 v29, 2, v29
	ds_bpermute_b32 v29, v29, v63
	v_cmp_lt_i32_e32 vcc, v31, v30
	s_waitcnt lgkmcnt(0)
	v_add_f32_e32 v29, v63, v29
	v_cndmask_b32_e32 v30, v48, v31, vcc
	v_lshlrev_b32_e32 v30, 2, v30
	ds_bpermute_b32 v30, v30, v29
	s_and_saveexec_b64 s[8:9], s[0:1]
	s_cbranch_execz .LBB0_82
	v_lshl_add_u64 v[32:33], v[2:3], 2, s[6:7]
	s_waitcnt lgkmcnt(0)
	v_add_f32_e32 v29, v29, v30
	global_atomic_add_f32 v[32:33], v29, off offset:64

; __device__ __forceinline__ void filt_item(const Params& p, int lsel, int tile, float* lds, int wave, float (&colsum)[16], bool flush) {
;     ...
;         for (int ct = 0; ct < 16; ++ct) {
;             const int col = wv * 256 + ct * 16 + l15;
;             const float* wp = p.hy_pos_w3 + (size_t)g * 2048 + col;
;             f32x4 acc = (f32x4){0.f, 0.f, 0.f, 0.f};
; #pragma unroll
;             for (int s_ = 0; s_ < 16; ++s_) acc = __builtin_amdgcn_mfma_f32_16x16x4f32(av[s_], wp[(size_t)s_ * 4 * 2048], acc, 0, 0, 0);
;             const float dec = fabsf(p.hy_decay[col]); float asum = 0.f;
; #pragma unroll
;             for (int r = 0; r < 4; ++r) { const float tn = (float)(t0 + 4 * g + r) * inv_lm1; acc[r] *= __expf(-tn * dec); asum += fabsf(acc[r]); }
;             *(f32x4*)(filt + (size_t)col * L + t0 + 4 * g) = acc;
;             colsum[ct] += asum;
;             if (flush) { float tot = colsum[ct]; tot += __shfl_xor(tot, 16); tot += __shfl_xor(tot, 32); if (g == 0) atomicAdd(normsum + col, tot); colsum[ct] = 0.f; }
.LBB0_83:
	s_waitcnt lgkmcnt(0)
	s_waitcnt vmcnt(17)
	v_mfma_f32_16x16x4_f32 v[30:33], v14, v234, 0
	global_load_dword v234, v[6:7], off offset:192
	global_load_dword v251, v[16:17], off offset:192
	s_waitcnt vmcnt(17)
	v_mfma_f32_16x16x4_f32 v[30:33], v15, v235, v[30:33]
	global_load_dword v235, v[204:205], off offset:192
	s_waitcnt vmcnt(17)
	v_mfma_f32_16x16x4_f32 v[30:33], v18, v236, v[30:33]
	global_load_dword v236, v[206:207], off offset:192
	s_waitcnt vmcnt(17)
	v_mfma_f32_16x16x4_f32 v[30:33], v19, v237, v[30:33]
	global_load_dword v237, v[208:209], off offset:192
	s_waitcnt vmcnt(17)
	v_mfma_f32_16x16x4_f32 v[30:33], v8, v238, v[30:33]
	global_load_dword v238, v[210:211], off offset:192
	s_waitcnt vmcnt(17)
	v_mfma_f32_16x16x4_f32 v[30:33], v9, v239, v[30:33]
	global_load_dword v239, v[212:213], off offset:192
	s_waitcnt vmcnt(17)
	v_mfma_f32_16x16x4_f32 v[30:33], v10, v240, v[30:33]
	global_load_dword v240, v[214:215], off offset:192
	s_waitcnt vmcnt(17)
	v_mfma_f32_16x16x4_f32 v[30:33], v11, v241, v[30:33]
	global_load_dword v241, v[216:217], off offset:192
	s_waitcnt vmcnt(17)
	v_mfma_f32_16x16x4_f32 v[30:33], v12, v242, v[30:33]
	global_load_dword v242, v[218:219], off offset:192
	v_or_b32_e32 v34, 32, v2
	v_ashrrev_i32_e32 v35, 31, v34
	v_lshlrev_b64 v[34:35], s24, v[34:35]
	v_lshl_add_u64 v[34:35], v[34:35], 2, v[4:5]
	s_and_b64 vcc, exec, s[4:5]
	s_waitcnt vmcnt(17)
	v_mfma_f32_16x16x4_f32 v[30:33], v13, v243, v[30:33]
	global_load_dword v243, v[220:221], off offset:192
	s_waitcnt vmcnt(17)
	v_mfma_f32_16x16x4_f32 v[30:33], v20, v244, v[30:33]
	global_load_dword v244, v[222:223], off offset:192
	s_waitcnt vmcnt(17)
	v_mfma_f32_16x16x4_f32 v[30:33], v21, v245, v[30:33]
	global_load_dword v245, v[224:225], off offset:192
	s_waitcnt vmcnt(17)
	v_mfma_f32_16x16x4_f32 v[30:33], v24, v246, v[30:33]
	global_load_dword v246, v[226:227], off offset:192
	s_waitcnt vmcnt(17)
	v_mfma_f32_16x16x4_f32 v[30:33], v25, v247, v[30:33]
	global_load_dword v247, v[228:229], off offset:192
	v_mul_f32_e64 v36, v28, |v250|
	s_waitcnt vmcnt(17)
	v_mfma_f32_16x16x4_f32 v[30:33], v22, v248, v[30:33]
	global_load_dword v248, v[230:231], off offset:192
	v_mul_f32_e64 v37, v27, |v250|
	v_mul_f32_e64 v38, v26, |v250|
	v_mul_f32_e64 v29, v0, |v250|
	v_mul_f32_e32 v36, 0x3fb8aa3b, v36
	v_mul_f32_e32 v37, 0x3fb8aa3b, v37
	v_mul_f32_e32 v38, 0x3fb8aa3b, v38
	v_mul_f32_e32 v29, 0x3fb8aa3b, v29
	s_waitcnt vmcnt(17)
	v_mfma_f32_16x16x4_f32 v[30:33], v23, v249, v[30:33]
	global_load_dword v249, v[232:233], off offset:192
	v_exp_f32_e32 v36, v36
	v_exp_f32_e32 v37, v37
	v_exp_f32_e32 v38, v38
	v_exp_f32_e32 v39, v29
	s_nop 5
	v_pk_mul_f32 v[30:31], v[30:31], v[36:37]
	v_pk_mul_f32 v[32:33], v[32:33], v[38:39]
	v_add_f32_e64 v29, |v30|, |v31|
	v_add_f32_e64 v29, |v32|, v29
	v_add_f32_e64 v29, |v33|, v29
	v_add_f32_e32 v62, v62, v29
	global_store_dwordx4 v[34:35], v[30:33], off
	s_cbranch_vccnz .LBB0_87
	s_nop 0
	v_and_b32_e32 v30, 64, v48
	v_xor_b32_e32 v29, 16, v48
	v_add_u32_e32 v30, 64, v30
	v_cmp_lt_i32_e32 vcc, v29, v30
	v_xor_b32_e32 v31, 32, v48
	s_nop 0
	v_cndmask_b32_e32 v29, v48, v29, vcc
	v_lshlrev_b32_e32 v29, 2, v29
	ds_bpermute_b32 v29, v29, v62
	v_cmp_lt_i32_e32 vcc, v31, v30
	s_waitcnt lgkmcnt(0)
	v_add_f32_e32 v29, v62, v29
	v_cndmask_b32_e32 v30, v48, v31, vcc
	v_lshlrev_b32_e32 v30, 2, v30
	ds_bpermute_b32 v30, v30, v29
	s_and_saveexec_b64 s[8:9], s[0:1]
	s_cbranch_execz .LBB0_86
	v_lshl_add_u64 v[32:33], v[2:3], 2, s[6:7]
	s_waitcnt lgkmcnt(0)
	v_add_f32_e32 v29, v29, v30
	global_atomic_add_f32 v[32:33], v29, off offset:128

; __device__ __forceinline__ void filt_item(const Params& p, int lsel, int tile, float* lds, int wave, float (&colsum)[16], bool flush) {
;     ...
;         for (int ct = 0; ct < 16; ++ct) {
;             const int col = wv * 256 + ct * 16 + l15;
;             const float* wp = p.hy_pos_w3 + (size_t)g * 2048 + col;
;             f32x4 acc = (f32x4){0.f, 0.f, 0.f, 0.f};
; #pragma unroll
;             for (int s_ = 0; s_ < 16; ++s_) acc = __builtin_amdgcn_mfma_f32_16x16x4f32(av[s_], wp[(size_t)s_ * 4 * 2048], acc, 0, 0, 0);
;             const float dec = fabsf(p.hy_decay[col]); float asum = 0.f;
; #pragma unroll
;             for (int r = 0; r < 4; ++r) { const float tn = (float)(t0 + 4 * g + r) * inv_lm1; acc[r] *= __expf(-tn * dec); asum += fabsf(acc[r]); }
;             *(f32x4*)(filt + (size_t)col * L + t0 + 4 * g) = acc;
;             colsum[ct] += asum;
;             if (flush) { float tot = colsum[ct]; tot += __shfl_xor(tot, 16); tot += __shfl_xor(tot, 32); if (g == 0) atomicAdd(normsum + col, tot); colsum[ct] = 0.f; }
;         }
.LBB0_87:
	s_waitcnt lgkmcnt(0)
	s_waitcnt vmcnt(17)
	v_mfma_f32_16x16x4_f32 v[30:33], v14, v234, 0
	global_load_dword v234, v[6:7], off offset:256
	global_load_dword v250, v[16:17], off offset:256
	s_waitcnt vmcnt(17)
	v_mfma_f32_16x16x4_f32 v[30:33], v15, v235, v[30:33]
	global_load_dword v235, v[204:205], off offset:256
	s_waitcnt vmcnt(17)
	v_mfma_f32_16x16x4_f32 v[30:33], v18, v236, v[30:33]
	global_load_dword v236, v[206:207], off offset:256
	s_waitcnt vmcnt(17)
	v_mfma_f32_16x16x4_f32 v[30:33], v19, v237, v[30:33]
	global_load_dword v237, v[208:209], off offset:256
	s_waitcnt vmcnt(17)
	v_mfma_f32_16x16x4_f32 v[30:33], v8, v238, v[30:33]
	global_load_dword v238, v[210:211], off offset:256
	s_waitcnt vmcnt(17)
	v_mfma_f32_16x16x4_f32 v[30:33], v9, v239, v[30:33]
	global_load_dword v239, v[212:213], off offset:256
	s_waitcnt vmcnt(17)
	v_mfma_f32_16x16x4_f32 v[30:33], v10, v240, v[30:33]
	global_load_dword v240, v[214:215], off offset:256
	s_waitcnt vmcnt(17)
	v_mfma_f32_16x16x4_f32 v[30:33], v11, v241, v[30:33]
	global_load_dword v241, v[216:217], off offset:256
	s_waitcnt vmcnt(17)
	v_mfma_f32_16x16x4_f32 v[30:33], v12, v242, v[30:33]
	global_load_dword v242, v[218:219], off offset:256
	v_or_b32_e32 v34, 48, v2
	v_ashrrev_i32_e32 v35, 31, v34
	v_lshlrev_b64 v[34:35], s24, v[34:35]
	v_lshl_add_u64 v[34:35], v[34:35], 2, v[4:5]
	s_and_b64 vcc, exec, s[4:5]
	s_waitcnt vmcnt(17)
	v_mfma_f32_16x16x4_f32 v[30:33], v13, v243, v[30:33]
	global_load_dword v243, v[220:221], off offset:256
	s_waitcnt vmcnt(17)
	v_mfma_f32_16x16x4_f32 v[30:33], v20, v244, v[30:33]
	global_load_dword v244, v[222:223], off offset:256
	s_waitcnt vmcnt(17)
	v_mfma_f32_16x16x4_f32 v[30:33], v21, v245, v[30:33]
	global_load_dword v245, v[224:225], off offset:256
	s_waitcnt vmcnt(17)
	v_mfma_f32_16x16x4_f32 v[30:33], v24, v246, v[30:33]
	global_load_dword v246, v[226:227], off offset:256
	s_waitcnt vmcnt(17)
	v_mfma_f32_16x16x4_f32 v[30:33], v25, v247, v[30:33]
	global_load_dword v247, v[228:229], off offset:256
	v_mul_f32_e64 v36, v28, |v251|
	s_waitcnt vmcnt(17)
	v_mfma_f32_16x16x4_f32 v[30:33], v22, v248, v[30:33]
	global_load_dword v248, v[230:231], off offset:256
	v_mul_f32_e64 v37, v27, |v251|
	v_mul_f32_e64 v38, v26, |v251|
	v_mul_f32_e64 v29, v0, |v251|
	v_mul_f32_e32 v36, 0x3fb8aa3b, v36
	v_mul_f32_e32 v37, 0x3fb8aa3b, v37
	v_mul_f32_e32 v38, 0x3fb8aa3b, v38
	v_mul_f32_e32 v29, 0x3fb8aa3b, v29
	s_waitcnt vmcnt(17)
	v_mfma_f32_16x16x4_f32 v[30:33], v23, v249, v[30:33]
	global_load_dword v249, v[232:233], off offset:256
	v_exp_f32_e32 v36, v36
	v_exp_f32_e32 v37, v37
	v_exp_f32_e32 v38, v38
	v_exp_f32_e32 v39, v29
	s_nop 5
	v_pk_mul_f32 v[30:31], v[30:31], v[36:37]
	v_pk_mul_f32 v[32:33], v[32:33], v[38:39]
	v_add_f32_e64 v29, |v30|, |v31|
	v_add_f32_e64 v29, |v32|, v29
	v_add_f32_e64 v29, |v33|, v29
	v_add_f32_e32 v61, v61, v29
	global_store_dwordx4 v[34:35], v[30:33], off
	s_cbranch_vccnz .LBB0_91
	s_nop 0
	v_and_b32_e32 v30, 64, v48
	v_xor_b32_e32 v29, 16, v48
	v_add_u32_e32 v30, 64, v30
	v_cmp_lt_i32_e32 vcc, v29, v30
	v_xor_b32_e32 v31, 32, v48
	s_nop 0
	v_cndmask_b32_e32 v29, v48, v29, vcc
	v_lshlrev_b32_e32 v29, 2, v29
	ds_bpermute_b32 v29, v29, v61
	v_cmp_lt_i32_e32 vcc, v31, v30
	s_waitcnt lgkmcnt(0)
	v_add_f32_e32 v29, v61, v29
	v_cndmask_b32_e32 v30, v48, v31, vcc
	v_lshlrev_b32_e32 v30, 2, v30
	ds_bpermute_b32 v30, v30, v29
	s_and_saveexec_b64 s[8:9], s[0:1]
	s_cbranch_execz .LBB0_90
	v_lshl_add_u64 v[32:33], v[2:3], 2, s[6:7]
	s_waitcnt lgkmcnt(0)
	v_add_f32_e32 v29, v29, v30
	global_atomic_add_f32 v[32:33], v29, off offset:192

; __device__ __forceinline__ void filt_item(const Params& p, int lsel, int tile, float* lds, int wave, float (&colsum)[16], bool flush) {
;     ...
;         for (int ct = 0; ct < 16; ++ct) {
;             const int col = wv * 256 + ct * 16 + l15;
;             const float* wp = p.hy_pos_w3 + (size_t)g * 2048 + col;
;             f32x4 acc = (f32x4){0.f, 0.f, 0.f, 0.f};
; #pragma unroll
;             for (int s_ = 0; s_ < 16; ++s_) acc = __builtin_amdgcn_mfma_f32_16x16x4f32(av[s_], wp[(size_t)s_ * 4 * 2048], acc, 0, 0, 0);
;             const float dec = fabsf(p.hy_decay[col]); float asum = 0.f;
; #pragma unroll
;             for (int r = 0; r < 4; ++r) { const float tn = (float)(t0 + 4 * g + r) * inv_lm1; acc[r] *= __expf(-tn * dec); asum += fabsf(acc[r]); }
;             *(f32x4*)(filt + (size_t)col * L + t0 + 4 * g) = acc;
;             colsum[ct] += asum;
;             if (flush) { float tot = colsum[ct]; tot += __shfl_xor(tot, 16); tot += __shfl_xor(tot, 32); if (g == 0) atomicAdd(normsum + col, tot); colsum[ct] = 0.f; }
;         }
.LBB0_91:
	s_waitcnt lgkmcnt(0)
	s_waitcnt vmcnt(17)
	v_mfma_f32_16x16x4_f32 v[30:33], v14, v234, 0
	global_load_dword v234, v[6:7], off offset:320
	global_load_dword v251, v[16:17], off offset:320
	s_waitcnt vmcnt(17)
	v_mfma_f32_16x16x4_f32 v[30:33], v15, v235, v[30:33]
	global_load_dword v235, v[204:205], off offset:320
	s_waitcnt vmcnt(17)
	v_mfma_f32_16x16x4_f32 v[30:33], v18, v236, v[30:33]
	global_load_dword v236, v[206:207], off offset:320
	s_waitcnt vmcnt(17)
	v_mfma_f32_16x16x4_f32 v[30:33], v19, v237, v[30:33]
	global_load_dword v237, v[208:209], off offset:320
	s_waitcnt vmcnt(17)
	v_mfma_f32_16x16x4_f32 v[30:33], v8, v238, v[30:33]
	global_load_dword v238, v[210:211], off offset:320
	s_waitcnt vmcnt(17)
	v_mfma_f32_16x16x4_f32 v[30:33], v9, v239, v[30:33]
	global_load_dword v239, v[212:213], off offset:320
	s_waitcnt vmcnt(17)
	v_mfma_f32_16x16x4_f32 v[30:33], v10, v240, v[30:33]
	global_load_dword v240, v[214:215], off offset:320
	s_waitcnt vmcnt(17)
	v_mfma_f32_16x16x4_f32 v[30:33], v11, v241, v[30:33]
	global_load_dword v241, v[216:217], off offset:320
	s_waitcnt vmcnt(17)
	v_mfma_f32_16x16x4_f32 v[30:33], v12, v242, v[30:33]
	global_load_dword v242, v[218:219], off offset:320
	v_or_b32_e32 v34, 64, v2
	v_ashrrev_i32_e32 v35, 31, v34
	v_lshlrev_b64 v[34:35], s24, v[34:35]
	v_lshl_add_u64 v[34:35], v[34:35], 2, v[4:5]
	s_and_b64 vcc, exec, s[4:5]
	s_waitcnt vmcnt(17)
	v_mfma_f32_16x16x4_f32 v[30:33], v13, v243, v[30:33]
	global_load_dword v243, v[220:221], off offset:320
	s_waitcnt vmcnt(17)
	v_mfma_f32_16x16x4_f32 v[30:33], v20, v244, v[30:33]
	global_load_dword v244, v[222:223], off offset:320
	s_waitcnt vmcnt(17)
	v_mfma_f32_16x16x4_f32 v[30:33], v21, v245, v[30:33]
	global_load_dword v245, v[224:225], off offset:320
	s_waitcnt vmcnt(17)
	v_mfma_f32_16x16x4_f32 v[30:33], v24, v246, v[30:33]
	global_load_dword v246, v[226:227], off offset:320
	s_waitcnt vmcnt(17)
	v_mfma_f32_16x16x4_f32 v[30:33], v25, v247, v[30:33]
	global_load_dword v247, v[228:229], off offset:320
	v_mul_f32_e64 v36, v28, |v250|
	s_waitcnt vmcnt(17)
	v_mfma_f32_16x16x4_f32 v[30:33], v22, v248, v[30:33]
	global_load_dword v248, v[230:231], off offset:320
	v_mul_f32_e64 v37, v27, |v250|
	v_mul_f32_e64 v38, v26, |v250|
	v_mul_f32_e64 v29, v0, |v250|
	v_mul_f32_e32 v36, 0x3fb8aa3b, v36
	v_mul_f32_e32 v37, 0x3fb8aa3b, v37
	v_mul_f32_e32 v38, 0x3fb8aa3b, v38
	v_mul_f32_e32 v29, 0x3fb8aa3b, v29
	s_waitcnt vmcnt(17)
	v_mfma_f32_16x16x4_f32 v[30:33], v23, v249, v[30:33]
	global_load_dword v249, v[232:233], off offset:320
	v_exp_f32_e32 v36, v36
	v_exp_f32_e32 v37, v37
	v_exp_f32_e32 v38, v38
	v_exp_f32_e32 v39, v29
	s_nop 5
	v_pk_mul_f32 v[30:31], v[30:31], v[36:37]
	v_pk_mul_f32 v[32:33], v[32:33], v[38:39]
	v_add_f32_e64 v29, |v30|, |v31|
	v_add_f32_e64 v29, |v32|, v29
	v_add_f32_e64 v29, |v33|, v29
	v_add_f32_e32 v60, v60, v29
	global_store_dwordx4 v[34:35], v[30:33], off
	s_cbranch_vccnz .LBB0_95
	s_nop 0
	v_and_b32_e32 v30, 64, v48
	v_xor_b32_e32 v29, 16, v48
	v_add_u32_e32 v30, 64, v30
	v_cmp_lt_i32_e32 vcc, v29, v30
	v_xor_b32_e32 v31, 32, v48
	s_nop 0
	v_cndmask_b32_e32 v29, v48, v29, vcc
	v_lshlrev_b32_e32 v29, 2, v29
	ds_bpermute_b32 v29, v29, v60
	v_cmp_lt_i32_e32 vcc, v31, v30
	s_waitcnt lgkmcnt(0)
	v_add_f32_e32 v29, v60, v29
	v_cndmask_b32_e32 v30, v48, v31, vcc
	v_lshlrev_b32_e32 v30, 2, v30
	ds_bpermute_b32 v30, v30, v29
	s_and_saveexec_b64 s[8:9], s[0:1]
	s_cbranch_execz .LBB0_94
	v_lshl_add_u64 v[32:33], v[2:3], 2, s[6:7]
	s_waitcnt lgkmcnt(0)
	v_add_f32_e32 v29, v29, v30
	global_atomic_add_f32 v[32:33], v29, off offset:256

; __device__ __forceinline__ void filt_item(const Params& p, int lsel, int tile, float* lds, int wave, float (&colsum)[16], bool flush) {
;     ...
;         for (int ct = 0; ct < 16; ++ct) {
;             const int col = wv * 256 + ct * 16 + l15;
;             const float* wp = p.hy_pos_w3 + (size_t)g * 2048 + col;
;             f32x4 acc = (f32x4){0.f, 0.f, 0.f, 0.f};
; #pragma unroll
;             for (int s_ = 0; s_ < 16; ++s_) acc = __builtin_amdgcn_mfma_f32_16x16x4f32(av[s_], wp[(size_t)s_ * 4 * 2048], acc, 0, 0, 0);
;             const float dec = fabsf(p.hy_decay[col]); float asum = 0.f;
; #pragma unroll
;             for (int r = 0; r < 4; ++r) { const float tn = (float)(t0 + 4 * g + r) * inv_lm1; acc[r] *= __expf(-tn * dec); asum += fabsf(acc[r]); }
;             *(f32x4*)(filt + (size_t)col * L + t0 + 4 * g) = acc;
;             colsum[ct] += asum;
;             if (flush) { float tot = colsum[ct]; tot += __shfl_xor(tot, 16); tot += __shfl_xor(tot, 32); if (g == 0) atomicAdd(normsum + col, tot); colsum[ct] = 0.f; }
;         }
.LBB0_95:
	s_waitcnt lgkmcnt(0)
	s_waitcnt vmcnt(17)
	v_mfma_f32_16x16x4_f32 v[30:33], v14, v234, 0
	global_load_dword v234, v[6:7], off offset:384
	global_load_dword v250, v[16:17], off offset:384
	s_waitcnt vmcnt(17)
	v_mfma_f32_16x16x4_f32 v[30:33], v15, v235, v[30:33]
	global_load_dword v235, v[204:205], off offset:384
	s_waitcnt vmcnt(17)
	v_mfma_f32_16x16x4_f32 v[30:33], v18, v236, v[30:33]
	global_load_dword v236, v[206:207], off offset:384
	s_waitcnt vmcnt(17)
	v_mfma_f32_16x16x4_f32 v[30:33], v19, v237, v[30:33]
	global_load_dword v237, v[208:209], off offset:384
	s_waitcnt vmcnt(17)
	v_mfma_f32_16x16x4_f32 v[30:33], v8, v238, v[30:33]
	global_load_dword v238, v[210:211], off offset:384
	s_waitcnt vmcnt(17)
	v_mfma_f32_16x16x4_f32 v[30:33], v9, v239, v[30:33]
	global_load_dword v239, v[212:213], off offset:384
	s_waitcnt vmcnt(17)
	v_mfma_f32_16x16x4_f32 v[30:33], v10, v240, v[30:33]
	global_load_dword v240, v[214:215], off offset:384
	s_waitcnt vmcnt(17)
	v_mfma_f32_16x16x4_f32 v[30:33], v11, v241, v[30:33]
	global_load_dword v241, v[216:217], off offset:384
	s_waitcnt vmcnt(17)
	v_mfma_f32_16x16x4_f32 v[30:33], v12, v242, v[30:33]
	global_load_dword v242, v[218:219], off offset:384
	v_or_b32_e32 v34, 0x50, v2
	v_ashrrev_i32_e32 v35, 31, v34
	v_lshlrev_b64 v[34:35], s24, v[34:35]
	v_lshl_add_u64 v[34:35], v[34:35], 2, v[4:5]
	s_and_b64 vcc, exec, s[4:5]
	s_waitcnt vmcnt(17)
	v_mfma_f32_16x16x4_f32 v[30:33], v13, v243, v[30:33]
	global_load_dword v243, v[220:221], off offset:384
	s_waitcnt vmcnt(17)
	v_mfma_f32_16x16x4_f32 v[30:33], v20, v244, v[30:33]
	global_load_dword v244, v[222:223], off offset:384
	s_waitcnt vmcnt(17)
	v_mfma_f32_16x16x4_f32 v[30:33], v21, v245, v[30:33]
	global_load_dword v245, v[224:225], off offset:384
	s_waitcnt vmcnt(17)
	v_mfma_f32_16x16x4_f32 v[30:33], v24, v246, v[30:33]
	global_load_dword v246, v[226:227], off offset:384
	s_waitcnt vmcnt(17)
	v_mfma_f32_16x16x4_f32 v[30:33], v25, v247, v[30:33]
	global_load_dword v247, v[228:229], off offset:384
	v_mul_f32_e64 v36, v28, |v251|
	s_waitcnt vmcnt(17)
	v_mfma_f32_16x16x4_f32 v[30:33], v22, v248, v[30:33]
	global_load_dword v248, v[230:231], off offset:384
	v_mul_f32_e64 v37, v27, |v251|
	v_mul_f32_e64 v38, v26, |v251|
	v_mul_f32_e64 v29, v0, |v251|
	v_mul_f32_e32 v36, 0x3fb8aa3b, v36
	v_mul_f32_e32 v37, 0x3fb8aa3b, v37
	v_mul_f32_e32 v38, 0x3fb8aa3b, v38
	v_mul_f32_e32 v29, 0x3fb8aa3b, v29
	s_waitcnt vmcnt(17)
	v_mfma_f32_16x16x4_f32 v[30:33], v23, v249, v[30:33]
	global_load_dword v249, v[232:233], off offset:384
	v_exp_f32_e32 v36, v36
	v_exp_f32_e32 v37, v37
	v_exp_f32_e32 v38, v38
	v_exp_f32_e32 v39, v29
	s_nop 5
	v_pk_mul_f32 v[30:31], v[30:31], v[36:37]
	v_pk_mul_f32 v[32:33], v[32:33], v[38:39]
	v_add_f32_e64 v29, |v30|, |v31|
	v_add_f32_e64 v29, |v32|, v29
	v_add_f32_e64 v29, |v33|, v29
	v_add_f32_e32 v59, v59, v29
	global_store_dwordx4 v[34:35], v[30:33], off
	s_cbranch_vccnz .LBB0_99
	s_nop 0
	v_and_b32_e32 v30, 64, v48
	v_xor_b32_e32 v29, 16, v48
	v_add_u32_e32 v30, 64, v30
	v_cmp_lt_i32_e32 vcc, v29, v30
	v_xor_b32_e32 v31, 32, v48
	s_nop 0
	v_cndmask_b32_e32 v29, v48, v29, vcc
	v_lshlrev_b32_e32 v29, 2, v29
	ds_bpermute_b32 v29, v29, v59
	v_cmp_lt_i32_e32 vcc, v31, v30
	s_waitcnt lgkmcnt(0)
	v_add_f32_e32 v29, v59, v29
	v_cndmask_b32_e32 v30, v48, v31, vcc
	v_lshlrev_b32_e32 v30, 2, v30
	ds_bpermute_b32 v30, v30, v29
	s_and_saveexec_b64 s[8:9], s[0:1]
	s_cbranch_execz .LBB0_98
	v_lshl_add_u64 v[32:33], v[2:3], 2, s[6:7]
	s_waitcnt lgkmcnt(0)
	v_add_f32_e32 v29, v29, v30
	global_atomic_add_f32 v[32:33], v29, off offset:320

; __device__ __forceinline__ void filt_item(const Params& p, int lsel, int tile, float* lds, int wave, float (&colsum)[16], bool flush) {
;     ...
;         for (int ct = 0; ct < 16; ++ct) {
;             const int col = wv * 256 + ct * 16 + l15;
;             const float* wp = p.hy_pos_w3 + (size_t)g * 2048 + col;
;             f32x4 acc = (f32x4){0.f, 0.f, 0.f, 0.f};
; #pragma unroll
;             for (int s_ = 0; s_ < 16; ++s_) acc = __builtin_amdgcn_mfma_f32_16x16x4f32(av[s_], wp[(size_t)s_ * 4 * 2048], acc, 0, 0, 0);
;             const float dec = fabsf(p.hy_decay[col]); float asum = 0.f;
; #pragma unroll
;             for (int r = 0; r < 4; ++r) { const float tn = (float)(t0 + 4 * g + r) * inv_lm1; acc[r] *= __expf(-tn * dec); asum += fabsf(acc[r]); }
;             *(f32x4*)(filt + (size_t)col * L + t0 + 4 * g) = acc;
;             colsum[ct] += asum;
;             if (flush) { float tot = colsum[ct]; tot += __shfl_xor(tot, 16); tot += __shfl_xor(tot, 32); if (g == 0) atomicAdd(normsum + col, tot); colsum[ct] = 0.f; }
;         }
.LBB0_99:
	s_waitcnt lgkmcnt(0)
	s_waitcnt vmcnt(17)
	v_mfma_f32_16x16x4_f32 v[30:33], v14, v234, 0
	global_load_dword v234, v[6:7], off offset:448
	global_load_dword v251, v[16:17], off offset:448
	s_waitcnt vmcnt(17)
	v_mfma_f32_16x16x4_f32 v[30:33], v15, v235, v[30:33]
	global_load_dword v235, v[204:205], off offset:448
	s_waitcnt vmcnt(17)
	v_mfma_f32_16x16x4_f32 v[30:33], v18, v236, v[30:33]
	global_load_dword v236, v[206:207], off offset:448
	s_waitcnt vmcnt(17)
	v_mfma_f32_16x16x4_f32 v[30:33], v19, v237, v[30:33]
	global_load_dword v237, v[208:209], off offset:448
	s_waitcnt vmcnt(17)
	v_mfma_f32_16x16x4_f32 v[30:33], v8, v238, v[30:33]
	global_load_dword v238, v[210:211], off offset:448
	s_waitcnt vmcnt(17)
	v_mfma_f32_16x16x4_f32 v[30:33], v9, v239, v[30:33]
	global_load_dword v239, v[212:213], off offset:448
	s_waitcnt vmcnt(17)
	v_mfma_f32_16x16x4_f32 v[30:33], v10, v240, v[30:33]
	global_load_dword v240, v[214:215], off offset:448
	s_waitcnt vmcnt(17)
	v_mfma_f32_16x16x4_f32 v[30:33], v11, v241, v[30:33]
	global_load_dword v241, v[216:217], off offset:448
	s_waitcnt vmcnt(17)
	v_mfma_f32_16x16x4_f32 v[30:33], v12, v242, v[30:33]
	global_load_dword v242, v[218:219], off offset:448
	v_or_b32_e32 v34, 0x60, v2
	v_ashrrev_i32_e32 v35, 31, v34
	v_lshlrev_b64 v[34:35], s24, v[34:35]
	v_lshl_add_u64 v[34:35], v[34:35], 2, v[4:5]
	s_and_b64 vcc, exec, s[4:5]
	s_waitcnt vmcnt(17)
	v_mfma_f32_16x16x4_f32 v[30:33], v13, v243, v[30:33]
	global_load_dword v243, v[220:221], off offset:448
	s_waitcnt vmcnt(17)
	v_mfma_f32_16x16x4_f32 v[30:33], v20, v244, v[30:33]
	global_load_dword v244, v[222:223], off offset:448
	s_waitcnt vmcnt(17)
	v_mfma_f32_16x16x4_f32 v[30:33], v21, v245, v[30:33]
	global_load_dword v245, v[224:225], off offset:448
	s_waitcnt vmcnt(17)
	v_mfma_f32_16x16x4_f32 v[30:33], v24, v246, v[30:33]
	global_load_dword v246, v[226:227], off offset:448
	s_waitcnt vmcnt(17)
	v_mfma_f32_16x16x4_f32 v[30:33], v25, v247, v[30:33]
	global_load_dword v247, v[228:229], off offset:448
	v_mul_f32_e64 v36, v28, |v250|
	s_waitcnt vmcnt(17)
	v_mfma_f32_16x16x4_f32 v[30:33], v22, v248, v[30:33]
	global_load_dword v248, v[230:231], off offset:448
	v_mul_f32_e64 v37, v27, |v250|
	v_mul_f32_e64 v38, v26, |v250|
	v_mul_f32_e64 v29, v0, |v250|
	v_mul_f32_e32 v36, 0x3fb8aa3b, v36
	v_mul_f32_e32 v37, 0x3fb8aa3b, v37
	v_mul_f32_e32 v38, 0x3fb8aa3b, v38
	v_mul_f32_e32 v29, 0x3fb8aa3b, v29
	s_waitcnt vmcnt(17)
	v_mfma_f32_16x16x4_f32 v[30:33], v23, v249, v[30:33]
	global_load_dword v249, v[232:233], off offset:448
	v_exp_f32_e32 v36, v36
	v_exp_f32_e32 v37, v37
	v_exp_f32_e32 v38, v38
	v_exp_f32_e32 v39, v29
	s_nop 5
	v_pk_mul_f32 v[30:31], v[30:31], v[36:37]
	v_pk_mul_f32 v[32:33], v[32:33], v[38:39]
	v_add_f32_e64 v29, |v30|, |v31|
	v_add_f32_e64 v29, |v32|, v29
	v_add_f32_e64 v29, |v33|, v29
	v_add_f32_e32 v58, v58, v29
	global_store_dwordx4 v[34:35], v[30:33], off
	s_cbranch_vccnz .LBB0_103
	s_nop 0
	v_and_b32_e32 v30, 64, v48
	v_xor_b32_e32 v29, 16, v48
	v_add_u32_e32 v30, 64, v30
	v_cmp_lt_i32_e32 vcc, v29, v30
	v_xor_b32_e32 v31, 32, v48
	s_nop 0
	v_cndmask_b32_e32 v29, v48, v29, vcc
	v_lshlrev_b32_e32 v29, 2, v29
	ds_bpermute_b32 v29, v29, v58
	v_cmp_lt_i32_e32 vcc, v31, v30
	s_waitcnt lgkmcnt(0)
	v_add_f32_e32 v29, v58, v29
	v_cndmask_b32_e32 v30, v48, v31, vcc
	v_lshlrev_b32_e32 v30, 2, v30
	ds_bpermute_b32 v30, v30, v29
	s_and_saveexec_b64 s[8:9], s[0:1]
	s_cbranch_execz .LBB0_102
	v_lshl_add_u64 v[32:33], v[2:3], 2, s[6:7]
	s_waitcnt lgkmcnt(0)
	v_add_f32_e32 v29, v29, v30
	global_atomic_add_f32 v[32:33], v29, off offset:384

; __device__ __forceinline__ void filt_item(const Params& p, int lsel, int tile, float* lds, int wave, float (&colsum)[16], bool flush) {
;     ...
;         for (int ct = 0; ct < 16; ++ct) {
;             const int col = wv * 256 + ct * 16 + l15;
;             const float* wp = p.hy_pos_w3 + (size_t)g * 2048 + col;
;             f32x4 acc = (f32x4){0.f, 0.f, 0.f, 0.f};
; #pragma unroll
;             for (int s_ = 0; s_ < 16; ++s_) acc = __builtin_amdgcn_mfma_f32_16x16x4f32(av[s_], wp[(size_t)s_ * 4 * 2048], acc, 0, 0, 0);
;             const float dec = fabsf(p.hy_decay[col]); float asum = 0.f;
; #pragma unroll
;             for (int r = 0; r < 4; ++r) { const float tn = (float)(t0 + 4 * g + r) * inv_lm1; acc[r] *= __expf(-tn * dec); asum += fabsf(acc[r]); }
;             *(f32x4*)(filt + (size_t)col * L + t0 + 4 * g) = acc;
;             colsum[ct] += asum;
;             if (flush) { float tot = colsum[ct]; tot += __shfl_xor(tot, 16); tot += __shfl_xor(tot, 32); if (g == 0) atomicAdd(normsum + col, tot); colsum[ct] = 0.f; }
;         }
.LBB0_103:
	s_waitcnt lgkmcnt(0)
	s_waitcnt vmcnt(17)
	v_mfma_f32_16x16x4_f32 v[30:33], v14, v234, 0
	global_load_dword v234, v[6:7], off offset:512
	global_load_dword v250, v[16:17], off offset:512
	s_waitcnt vmcnt(17)
	v_mfma_f32_16x16x4_f32 v[30:33], v15, v235, v[30:33]
	global_load_dword v235, v[204:205], off offset:512
	s_waitcnt vmcnt(17)
	v_mfma_f32_16x16x4_f32 v[30:33], v18, v236, v[30:33]
	global_load_dword v236, v[206:207], off offset:512
	s_waitcnt vmcnt(17)
	v_mfma_f32_16x16x4_f32 v[30:33], v19, v237, v[30:33]
	global_load_dword v237, v[208:209], off offset:512
	s_waitcnt vmcnt(17)
	v_mfma_f32_16x16x4_f32 v[30:33], v8, v238, v[30:33]
	global_load_dword v238, v[210:211], off offset:512
	s_waitcnt vmcnt(17)
	v_mfma_f32_16x16x4_f32 v[30:33], v9, v239, v[30:33]
	global_load_dword v239, v[212:213], off offset:512
	s_waitcnt vmcnt(17)
	v_mfma_f32_16x16x4_f32 v[30:33], v10, v240, v[30:33]
	global_load_dword v240, v[214:215], off offset:512
	s_waitcnt vmcnt(17)
	v_mfma_f32_16x16x4_f32 v[30:33], v11, v241, v[30:33]
	global_load_dword v241, v[216:217], off offset:512
	s_waitcnt vmcnt(17)
	v_mfma_f32_16x16x4_f32 v[30:33], v12, v242, v[30:33]
	global_load_dword v242, v[218:219], off offset:512
	v_or_b32_e32 v34, 0x70, v2
	v_ashrrev_i32_e32 v35, 31, v34
	v_lshlrev_b64 v[34:35], s24, v[34:35]
	v_lshl_add_u64 v[34:35], v[34:35], 2, v[4:5]
	s_and_b64 vcc, exec, s[4:5]
	s_waitcnt vmcnt(17)
	v_mfma_f32_16x16x4_f32 v[30:33], v13, v243, v[30:33]
	global_load_dword v243, v[220:221], off offset:512
	s_waitcnt vmcnt(17)
	v_mfma_f32_16x16x4_f32 v[30:33], v20, v244, v[30:33]
	global_load_dword v244, v[222:223], off offset:512
	s_waitcnt vmcnt(17)
	v_mfma_f32_16x16x4_f32 v[30:33], v21, v245, v[30:33]
	global_load_dword v245, v[224:225], off offset:512
	s_waitcnt vmcnt(17)
	v_mfma_f32_16x16x4_f32 v[30:33], v24, v246, v[30:33]
	global_load_dword v246, v[226:227], off offset:512
	s_waitcnt vmcnt(17)
	v_mfma_f32_16x16x4_f32 v[30:33], v25, v247, v[30:33]
	global_load_dword v247, v[228:229], off offset:512
	v_mul_f32_e64 v36, v28, |v251|
	s_waitcnt vmcnt(17)
	v_mfma_f32_16x16x4_f32 v[30:33], v22, v248, v[30:33]
	global_load_dword v248, v[230:231], off offset:512
	v_mul_f32_e64 v37, v27, |v251|
	v_mul_f32_e64 v38, v26, |v251|
	v_mul_f32_e64 v29, v0, |v251|
	v_mul_f32_e32 v36, 0x3fb8aa3b, v36
	v_mul_f32_e32 v37, 0x3fb8aa3b, v37
	v_mul_f32_e32 v38, 0x3fb8aa3b, v38
	v_mul_f32_e32 v29, 0x3fb8aa3b, v29
	s_waitcnt vmcnt(17)
	v_mfma_f32_16x16x4_f32 v[30:33], v23, v249, v[30:33]
	global_load_dword v249, v[232:233], off offset:512
	v_exp_f32_e32 v36, v36
	v_exp_f32_e32 v37, v37
	v_exp_f32_e32 v38, v38
	v_exp_f32_e32 v39, v29
	s_nop 5
	v_pk_mul_f32 v[30:31], v[30:31], v[36:37]
	v_pk_mul_f32 v[32:33], v[32:33], v[38:39]
	v_add_f32_e64 v29, |v30|, |v31|
	v_add_f32_e64 v29, |v32|, v29
	v_add_f32_e64 v29, |v33|, v29
	v_add_f32_e32 v57, v57, v29
	global_store_dwordx4 v[34:35], v[30:33], off
	s_cbranch_vccnz .LBB0_107
	s_nop 0
	v_and_b32_e32 v30, 64, v48
	v_xor_b32_e32 v29, 16, v48
	v_add_u32_e32 v30, 64, v30
	v_cmp_lt_i32_e32 vcc, v29, v30
	v_xor_b32_e32 v31, 32, v48
	s_nop 0
	v_cndmask_b32_e32 v29, v48, v29, vcc
	v_lshlrev_b32_e32 v29, 2, v29
	ds_bpermute_b32 v29, v29, v57
	v_cmp_lt_i32_e32 vcc, v31, v30
	s_waitcnt lgkmcnt(0)
	v_add_f32_e32 v29, v57, v29
	v_cndmask_b32_e32 v30, v48, v31, vcc
	v_lshlrev_b32_e32 v30, 2, v30
	ds_bpermute_b32 v30, v30, v29
	s_and_saveexec_b64 s[8:9], s[0:1]
	s_cbranch_execz .LBB0_106
	v_lshl_add_u64 v[32:33], v[2:3], 2, s[6:7]
	s_waitcnt lgkmcnt(0)
	v_add_f32_e32 v29, v29, v30
	global_atomic_add_f32 v[32:33], v29, off offset:448

; __device__ __forceinline__ void filt_item(const Params& p, int lsel, int tile, float* lds, int wave, float (&colsum)[16], bool flush) {
;     ...
;         for (int ct = 0; ct < 16; ++ct) {
;             const int col = wv * 256 + ct * 16 + l15;
;             const float* wp = p.hy_pos_w3 + (size_t)g * 2048 + col;
;             f32x4 acc = (f32x4){0.f, 0.f, 0.f, 0.f};
; #pragma unroll
;             for (int s_ = 0; s_ < 16; ++s_) acc = __builtin_amdgcn_mfma_f32_16x16x4f32(av[s_], wp[(size_t)s_ * 4 * 2048], acc, 0, 0, 0);
;             const float dec = fabsf(p.hy_decay[col]); float asum = 0.f;
; #pragma unroll
;             for (int r = 0; r < 4; ++r) { const float tn = (float)(t0 + 4 * g + r) * inv_lm1; acc[r] *= __expf(-tn * dec); asum += fabsf(acc[r]); }
;             *(f32x4*)(filt + (size_t)col * L + t0 + 4 * g) = acc;
;             colsum[ct] += asum;
;             if (flush) { float tot = colsum[ct]; tot += __shfl_xor(tot, 16); tot += __shfl_xor(tot, 32); if (g == 0) atomicAdd(normsum + col, tot); colsum[ct] = 0.f; }
;         }
.LBB0_107:
	s_waitcnt lgkmcnt(0)
	s_waitcnt vmcnt(17)
	v_mfma_f32_16x16x4_f32 v[30:33], v14, v234, 0
	global_load_dword v234, v[6:7], off offset:576
	global_load_dword v251, v[16:17], off offset:576
	s_waitcnt vmcnt(17)
	v_mfma_f32_16x16x4_f32 v[30:33], v15, v235, v[30:33]
	global_load_dword v235, v[204:205], off offset:576
	s_waitcnt vmcnt(17)
	v_mfma_f32_16x16x4_f32 v[30:33], v18, v236, v[30:33]
	global_load_dword v236, v[206:207], off offset:576
	s_waitcnt vmcnt(17)
	v_mfma_f32_16x16x4_f32 v[30:33], v19, v237, v[30:33]
	global_load_dword v237, v[208:209], off offset:576
	s_waitcnt vmcnt(17)
	v_mfma_f32_16x16x4_f32 v[30:33], v8, v238, v[30:33]
	global_load_dword v238, v[210:211], off offset:576
	s_waitcnt vmcnt(17)
	v_mfma_f32_16x16x4_f32 v[30:33], v9, v239, v[30:33]
	global_load_dword v239, v[212:213], off offset:576
	s_waitcnt vmcnt(17)
	v_mfma_f32_16x16x4_f32 v[30:33], v10, v240, v[30:33]
	global_load_dword v240, v[214:215], off offset:576
	s_waitcnt vmcnt(17)
	v_mfma_f32_16x16x4_f32 v[30:33], v11, v241, v[30:33]
	global_load_dword v241, v[216:217], off offset:576
	s_waitcnt vmcnt(17)
	v_mfma_f32_16x16x4_f32 v[30:33], v12, v242, v[30:33]
	global_load_dword v242, v[218:219], off offset:576
	v_or_b32_e32 v34, 0x80, v2
	v_ashrrev_i32_e32 v35, 31, v34
	v_lshlrev_b64 v[34:35], s24, v[34:35]
	v_lshl_add_u64 v[34:35], v[34:35], 2, v[4:5]
	s_and_b64 vcc, exec, s[4:5]
	s_waitcnt vmcnt(17)
	v_mfma_f32_16x16x4_f32 v[30:33], v13, v243, v[30:33]
	global_load_dword v243, v[220:221], off offset:576
	s_waitcnt vmcnt(17)
	v_mfma_f32_16x16x4_f32 v[30:33], v20, v244, v[30:33]
	global_load_dword v244, v[222:223], off offset:576
	s_waitcnt vmcnt(17)
	v_mfma_f32_16x16x4_f32 v[30:33], v21, v245, v[30:33]
	global_load_dword v245, v[224:225], off offset:576
	s_waitcnt vmcnt(17)
	v_mfma_f32_16x16x4_f32 v[30:33], v24, v246, v[30:33]
	global_load_dword v246, v[226:227], off offset:576
	s_waitcnt vmcnt(17)
	v_mfma_f32_16x16x4_f32 v[30:33], v25, v247, v[30:33]
	global_load_dword v247, v[228:229], off offset:576
	v_mul_f32_e64 v36, v28, |v250|
	s_waitcnt vmcnt(17)
	v_mfma_f32_16x16x4_f32 v[30:33], v22, v248, v[30:33]
	global_load_dword v248, v[230:231], off offset:576
	v_mul_f32_e64 v37, v27, |v250|
	v_mul_f32_e64 v38, v26, |v250|
	v_mul_f32_e64 v29, v0, |v250|
	v_mul_f32_e32 v36, 0x3fb8aa3b, v36
	v_mul_f32_e32 v37, 0x3fb8aa3b, v37
	v_mul_f32_e32 v38, 0x3fb8aa3b, v38
	v_mul_f32_e32 v29, 0x3fb8aa3b, v29
	s_waitcnt vmcnt(17)
	v_mfma_f32_16x16x4_f32 v[30:33], v23, v249, v[30:33]
	global_load_dword v249, v[232:233], off offset:576
	v_exp_f32_e32 v36, v36
	v_exp_f32_e32 v37, v37
	v_exp_f32_e32 v38, v38
	v_exp_f32_e32 v39, v29
	s_nop 5
	v_pk_mul_f32 v[30:31], v[30:31], v[36:37]
	v_pk_mul_f32 v[32:33], v[32:33], v[38:39]
	v_add_f32_e64 v29, |v30|, |v31|
	v_add_f32_e64 v29, |v32|, v29
	v_add_f32_e64 v29, |v33|, v29
	v_add_f32_e32 v56, v56, v29
	global_store_dwordx4 v[34:35], v[30:33], off
	s_cbranch_vccnz .LBB0_111
	s_nop 0
	v_and_b32_e32 v30, 64, v48
	v_xor_b32_e32 v29, 16, v48
	v_add_u32_e32 v30, 64, v30
	v_cmp_lt_i32_e32 vcc, v29, v30
	v_xor_b32_e32 v31, 32, v48
	s_nop 0
	v_cndmask_b32_e32 v29, v48, v29, vcc
	v_lshlrev_b32_e32 v29, 2, v29
	ds_bpermute_b32 v29, v29, v56
	v_cmp_lt_i32_e32 vcc, v31, v30
	s_waitcnt lgkmcnt(0)
	v_add_f32_e32 v29, v56, v29
	v_cndmask_b32_e32 v30, v48, v31, vcc
	v_lshlrev_b32_e32 v30, 2, v30
	ds_bpermute_b32 v30, v30, v29
	s_and_saveexec_b64 s[8:9], s[0:1]
	s_cbranch_execz .LBB0_110
	v_lshl_add_u64 v[32:33], v[2:3], 2, s[6:7]
	s_waitcnt lgkmcnt(0)
	v_add_f32_e32 v29, v29, v30
	global_atomic_add_f32 v[32:33], v29, off offset:512

; __device__ __forceinline__ void filt_item(const Params& p, int lsel, int tile, float* lds, int wave, float (&colsum)[16], bool flush) {
;     ...
;         for (int ct = 0; ct < 16; ++ct) {
;             const int col = wv * 256 + ct * 16 + l15;
;             const float* wp = p.hy_pos_w3 + (size_t)g * 2048 + col;
;             f32x4 acc = (f32x4){0.f, 0.f, 0.f, 0.f};
; #pragma unroll
;             for (int s_ = 0; s_ < 16; ++s_) acc = __builtin_amdgcn_mfma_f32_16x16x4f32(av[s_], wp[(size_t)s_ * 4 * 2048], acc, 0, 0, 0);
;             const float dec = fabsf(p.hy_decay[col]); float asum = 0.f;
; #pragma unroll
;             for (int r = 0; r < 4; ++r) { const float tn = (float)(t0 + 4 * g + r) * inv_lm1; acc[r] *= __expf(-tn * dec); asum += fabsf(acc[r]); }
;             *(f32x4*)(filt + (size_t)col * L + t0 + 4 * g) = acc;
;             colsum[ct] += asum;
;             if (flush) { float tot = colsum[ct]; tot += __shfl_xor(tot, 16); tot += __shfl_xor(tot, 32); if (g == 0) atomicAdd(normsum + col, tot); colsum[ct] = 0.f; }
;         }
.LBB0_111:
	s_waitcnt lgkmcnt(0)
	s_waitcnt vmcnt(17)
	v_mfma_f32_16x16x4_f32 v[30:33], v14, v234, 0
	global_load_dword v234, v[6:7], off offset:640
	global_load_dword v250, v[16:17], off offset:640
	s_waitcnt vmcnt(17)
	v_mfma_f32_16x16x4_f32 v[30:33], v15, v235, v[30:33]
	global_load_dword v235, v[204:205], off offset:640
	s_waitcnt vmcnt(17)
	v_mfma_f32_16x16x4_f32 v[30:33], v18, v236, v[30:33]
	global_load_dword v236, v[206:207], off offset:640
	s_waitcnt vmcnt(17)
	v_mfma_f32_16x16x4_f32 v[30:33], v19, v237, v[30:33]
	global_load_dword v237, v[208:209], off offset:640
	s_waitcnt vmcnt(17)
	v_mfma_f32_16x16x4_f32 v[30:33], v8, v238, v[30:33]
	global_load_dword v238, v[210:211], off offset:640
	s_waitcnt vmcnt(17)
	v_mfma_f32_16x16x4_f32 v[30:33], v9, v239, v[30:33]
	global_load_dword v239, v[212:213], off offset:640
	s_waitcnt vmcnt(17)
	v_mfma_f32_16x16x4_f32 v[30:33], v10, v240, v[30:33]
	global_load_dword v240, v[214:215], off offset:640
	s_waitcnt vmcnt(17)
	v_mfma_f32_16x16x4_f32 v[30:33], v11, v241, v[30:33]
	global_load_dword v241, v[216:217], off offset:640
	s_waitcnt vmcnt(17)
	v_mfma_f32_16x16x4_f32 v[30:33], v12, v242, v[30:33]
	global_load_dword v242, v[218:219], off offset:640
	v_or_b32_e32 v34, 0x90, v2
	v_ashrrev_i32_e32 v35, 31, v34
	v_lshlrev_b64 v[34:35], s24, v[34:35]
	v_lshl_add_u64 v[34:35], v[34:35], 2, v[4:5]
	s_and_b64 vcc, exec, s[4:5]
	s_waitcnt vmcnt(17)
	v_mfma_f32_16x16x4_f32 v[30:33], v13, v243, v[30:33]
	global_load_dword v243, v[220:221], off offset:640
	s_waitcnt vmcnt(17)
	v_mfma_f32_16x16x4_f32 v[30:33], v20, v244, v[30:33]
	global_load_dword v244, v[222:223], off offset:640
	s_waitcnt vmcnt(17)
	v_mfma_f32_16x16x4_f32 v[30:33], v21, v245, v[30:33]
	global_load_dword v245, v[224:225], off offset:640
	s_waitcnt vmcnt(17)
	v_mfma_f32_16x16x4_f32 v[30:33], v24, v246, v[30:33]
	global_load_dword v246, v[226:227], off offset:640
	s_waitcnt vmcnt(17)
	v_mfma_f32_16x16x4_f32 v[30:33], v25, v247, v[30:33]
	global_load_dword v247, v[228:229], off offset:640
	v_mul_f32_e64 v36, v28, |v251|
	s_waitcnt vmcnt(17)
	v_mfma_f32_16x16x4_f32 v[30:33], v22, v248, v[30:33]
	global_load_dword v248, v[230:231], off offset:640
	v_mul_f32_e64 v37, v27, |v251|
	v_mul_f32_e64 v38, v26, |v251|
	v_mul_f32_e64 v29, v0, |v251|
	v_mul_f32_e32 v36, 0x3fb8aa3b, v36
	v_mul_f32_e32 v37, 0x3fb8aa3b, v37
	v_mul_f32_e32 v38, 0x3fb8aa3b, v38
	v_mul_f32_e32 v29, 0x3fb8aa3b, v29
	s_waitcnt vmcnt(17)
	v_mfma_f32_16x16x4_f32 v[30:33], v23, v249, v[30:33]
	global_load_dword v249, v[232:233], off offset:640
	v_exp_f32_e32 v36, v36
	v_exp_f32_e32 v37, v37
	v_exp_f32_e32 v38, v38
	v_exp_f32_e32 v39, v29
	s_nop 5
	v_pk_mul_f32 v[30:31], v[30:31], v[36:37]
	v_pk_mul_f32 v[32:33], v[32:33], v[38:39]
	v_add_f32_e64 v29, |v30|, |v31|
	v_add_f32_e64 v29, |v32|, v29
	v_add_f32_e64 v29, |v33|, v29
	v_add_f32_e32 v55, v55, v29
	global_store_dwordx4 v[34:35], v[30:33], off
	s_cbranch_vccnz .LBB0_115
	s_nop 0
	v_and_b32_e32 v30, 64, v48
	v_xor_b32_e32 v29, 16, v48
	v_add_u32_e32 v30, 64, v30
	v_cmp_lt_i32_e32 vcc, v29, v30
	v_xor_b32_e32 v31, 32, v48
	s_nop 0
	v_cndmask_b32_e32 v29, v48, v29, vcc
	v_lshlrev_b32_e32 v29, 2, v29
	ds_bpermute_b32 v29, v29, v55
	v_cmp_lt_i32_e32 vcc, v31, v30
	s_waitcnt lgkmcnt(0)
	v_add_f32_e32 v29, v55, v29
	v_cndmask_b32_e32 v30, v48, v31, vcc
	v_lshlrev_b32_e32 v30, 2, v30
	ds_bpermute_b32 v30, v30, v29
	s_and_saveexec_b64 s[8:9], s[0:1]
	s_cbranch_execz .LBB0_114
	v_lshl_add_u64 v[32:33], v[2:3], 2, s[6:7]
	s_waitcnt lgkmcnt(0)
	v_add_f32_e32 v29, v29, v30
	global_atomic_add_f32 v[32:33], v29, off offset:576

; __device__ __forceinline__ void filt_item(const Params& p, int lsel, int tile, float* lds, int wave, float (&colsum)[16], bool flush) {
;     ...
;         for (int ct = 0; ct < 16; ++ct) {
;             const int col = wv * 256 + ct * 16 + l15;
;             const float* wp = p.hy_pos_w3 + (size_t)g * 2048 + col;
;             f32x4 acc = (f32x4){0.f, 0.f, 0.f, 0.f};
; #pragma unroll
;             for (int s_ = 0; s_ < 16; ++s_) acc = __builtin_amdgcn_mfma_f32_16x16x4f32(av[s_], wp[(size_t)s_ * 4 * 2048], acc, 0, 0, 0);
;             const float dec = fabsf(p.hy_decay[col]); float asum = 0.f;
; #pragma unroll
;             for (int r = 0; r < 4; ++r) { const float tn = (float)(t0 + 4 * g + r) * inv_lm1; acc[r] *= __expf(-tn * dec); asum += fabsf(acc[r]); }
;             *(f32x4*)(filt + (size_t)col * L + t0 + 4 * g) = acc;
;             colsum[ct] += asum;
;             if (flush) { float tot = colsum[ct]; tot += __shfl_xor(tot, 16); tot += __shfl_xor(tot, 32); if (g == 0) atomicAdd(normsum + col, tot); colsum[ct] = 0.f; }
;         }
.LBB0_115:
	s_waitcnt lgkmcnt(0)
	s_waitcnt vmcnt(17)
	v_mfma_f32_16x16x4_f32 v[30:33], v14, v234, 0
	global_load_dword v234, v[6:7], off offset:704
	global_load_dword v251, v[16:17], off offset:704
	s_waitcnt vmcnt(17)
	v_mfma_f32_16x16x4_f32 v[30:33], v15, v235, v[30:33]
	global_load_dword v235, v[204:205], off offset:704
	s_waitcnt vmcnt(17)
	v_mfma_f32_16x16x4_f32 v[30:33], v18, v236, v[30:33]
	global_load_dword v236, v[206:207], off offset:704
	s_waitcnt vmcnt(17)
	v_mfma_f32_16x16x4_f32 v[30:33], v19, v237, v[30:33]
	global_load_dword v237, v[208:209], off offset:704
	s_waitcnt vmcnt(17)
	v_mfma_f32_16x16x4_f32 v[30:33], v8, v238, v[30:33]
	global_load_dword v238, v[210:211], off offset:704
	s_waitcnt vmcnt(17)
	v_mfma_f32_16x16x4_f32 v[30:33], v9, v239, v[30:33]
	global_load_dword v239, v[212:213], off offset:704
	s_waitcnt vmcnt(17)
	v_mfma_f32_16x16x4_f32 v[30:33], v10, v240, v[30:33]
	global_load_dword v240, v[214:215], off offset:704
	s_waitcnt vmcnt(17)
	v_mfma_f32_16x16x4_f32 v[30:33], v11, v241, v[30:33]
	global_load_dword v241, v[216:217], off offset:704
	s_waitcnt vmcnt(17)
	v_mfma_f32_16x16x4_f32 v[30:33], v12, v242, v[30:33]
	global_load_dword v242, v[218:219], off offset:704
	v_or_b32_e32 v34, 0xa0, v2
	v_ashrrev_i32_e32 v35, 31, v34
	v_lshlrev_b64 v[34:35], s24, v[34:35]
	v_lshl_add_u64 v[34:35], v[34:35], 2, v[4:5]
	s_and_b64 vcc, exec, s[4:5]
	s_waitcnt vmcnt(17)
	v_mfma_f32_16x16x4_f32 v[30:33], v13, v243, v[30:33]
	global_load_dword v243, v[220:221], off offset:704
	s_waitcnt vmcnt(17)
	v_mfma_f32_16x16x4_f32 v[30:33], v20, v244, v[30:33]
	global_load_dword v244, v[222:223], off offset:704
	s_waitcnt vmcnt(17)
	v_mfma_f32_16x16x4_f32 v[30:33], v21, v245, v[30:33]
	global_load_dword v245, v[224:225], off offset:704
	s_waitcnt vmcnt(17)
	v_mfma_f32_16x16x4_f32 v[30:33], v24, v246, v[30:33]
	global_load_dword v246, v[226:227], off offset:704
	s_waitcnt vmcnt(17)
	v_mfma_f32_16x16x4_f32 v[30:33], v25, v247, v[30:33]
	global_load_dword v247, v[228:229], off offset:704
	v_mul_f32_e64 v36, v28, |v250|
	s_waitcnt vmcnt(17)
	v_mfma_f32_16x16x4_f32 v[30:33], v22, v248, v[30:33]
	global_load_dword v248, v[230:231], off offset:704
	v_mul_f32_e64 v37, v27, |v250|
	v_mul_f32_e64 v38, v26, |v250|
	v_mul_f32_e64 v29, v0, |v250|
	v_mul_f32_e32 v36, 0x3fb8aa3b, v36
	v_mul_f32_e32 v37, 0x3fb8aa3b, v37
	v_mul_f32_e32 v38, 0x3fb8aa3b, v38
	v_mul_f32_e32 v29, 0x3fb8aa3b, v29
	s_waitcnt vmcnt(17)
	v_mfma_f32_16x16x4_f32 v[30:33], v23, v249, v[30:33]
	global_load_dword v249, v[232:233], off offset:704
	v_exp_f32_e32 v36, v36
	v_exp_f32_e32 v37, v37
	v_exp_f32_e32 v38, v38
	v_exp_f32_e32 v39, v29
	s_nop 5
	v_pk_mul_f32 v[30:31], v[30:31], v[36:37]
	v_pk_mul_f32 v[32:33], v[32:33], v[38:39]
	v_add_f32_e64 v29, |v30|, |v31|
	v_add_f32_e64 v29, |v32|, v29
	v_add_f32_e64 v29, |v33|, v29
	v_add_f32_e32 v54, v54, v29
	global_store_dwordx4 v[34:35], v[30:33], off
	s_cbranch_vccnz .LBB0_119
	s_nop 0
	v_and_b32_e32 v30, 64, v48
	v_xor_b32_e32 v29, 16, v48
	v_add_u32_e32 v30, 64, v30
	v_cmp_lt_i32_e32 vcc, v29, v30
	v_xor_b32_e32 v31, 32, v48
	s_nop 0
	v_cndmask_b32_e32 v29, v48, v29, vcc
	v_lshlrev_b32_e32 v29, 2, v29
	ds_bpermute_b32 v29, v29, v54
	v_cmp_lt_i32_e32 vcc, v31, v30
	s_waitcnt lgkmcnt(0)
	v_add_f32_e32 v29, v54, v29
	v_cndmask_b32_e32 v30, v48, v31, vcc
	v_lshlrev_b32_e32 v30, 2, v30
	ds_bpermute_b32 v30, v30, v29
	s_and_saveexec_b64 s[8:9], s[0:1]
	s_cbranch_execz .LBB0_118
	v_lshl_add_u64 v[32:33], v[2:3], 2, s[6:7]
	s_waitcnt lgkmcnt(0)
	v_add_f32_e32 v29, v29, v30
	global_atomic_add_f32 v[32:33], v29, off offset:640

; __device__ __forceinline__ void filt_item(const Params& p, int lsel, int tile, float* lds, int wave, float (&colsum)[16], bool flush) {
;     ...
;         for (int ct = 0; ct < 16; ++ct) {
;             const int col = wv * 256 + ct * 16 + l15;
;             const float* wp = p.hy_pos_w3 + (size_t)g * 2048 + col;
;             f32x4 acc = (f32x4){0.f, 0.f, 0.f, 0.f};
; #pragma unroll
;             for (int s_ = 0; s_ < 16; ++s_) acc = __builtin_amdgcn_mfma_f32_16x16x4f32(av[s_], wp[(size_t)s_ * 4 * 2048], acc, 0, 0, 0);
;             const float dec = fabsf(p.hy_decay[col]); float asum = 0.f;
; #pragma unroll
;             for (int r = 0; r < 4; ++r) { const float tn = (float)(t0 + 4 * g + r) * inv_lm1; acc[r] *= __expf(-tn * dec); asum += fabsf(acc[r]); }
;             *(f32x4*)(filt + (size_t)col * L + t0 + 4 * g) = acc;
;             colsum[ct] += asum;
;             if (flush) { float tot = colsum[ct]; tot += __shfl_xor(tot, 16); tot += __shfl_xor(tot, 32); if (g == 0) atomicAdd(normsum + col, tot); colsum[ct] = 0.f; }
;         }
.LBB0_119:
	s_waitcnt lgkmcnt(0)
	s_waitcnt vmcnt(17)
	v_mfma_f32_16x16x4_f32 v[30:33], v14, v234, 0
	global_load_dword v234, v[6:7], off offset:768
	global_load_dword v250, v[16:17], off offset:768
	s_waitcnt vmcnt(17)
	v_mfma_f32_16x16x4_f32 v[30:33], v15, v235, v[30:33]
	global_load_dword v235, v[204:205], off offset:768
	s_waitcnt vmcnt(17)
	v_mfma_f32_16x16x4_f32 v[30:33], v18, v236, v[30:33]
	global_load_dword v236, v[206:207], off offset:768
	s_waitcnt vmcnt(17)
	v_mfma_f32_16x16x4_f32 v[30:33], v19, v237, v[30:33]
	global_load_dword v237, v[208:209], off offset:768
	s_waitcnt vmcnt(17)
	v_mfma_f32_16x16x4_f32 v[30:33], v8, v238, v[30:33]
	global_load_dword v238, v[210:211], off offset:768
	s_waitcnt vmcnt(17)
	v_mfma_f32_16x16x4_f32 v[30:33], v9, v239, v[30:33]
	global_load_dword v239, v[212:213], off offset:768
	s_waitcnt vmcnt(17)
	v_mfma_f32_16x16x4_f32 v[30:33], v10, v240, v[30:33]
	global_load_dword v240, v[214:215], off offset:768
	s_waitcnt vmcnt(17)
	v_mfma_f32_16x16x4_f32 v[30:33], v11, v241, v[30:33]
	global_load_dword v241, v[216:217], off offset:768
	s_waitcnt vmcnt(17)
	v_mfma_f32_16x16x4_f32 v[30:33], v12, v242, v[30:33]
	global_load_dword v242, v[218:219], off offset:768
	v_or_b32_e32 v34, 0xb0, v2
	v_ashrrev_i32_e32 v35, 31, v34
	v_lshlrev_b64 v[34:35], s24, v[34:35]
	v_lshl_add_u64 v[34:35], v[34:35], 2, v[4:5]
	s_and_b64 vcc, exec, s[4:5]
	s_waitcnt vmcnt(17)
	v_mfma_f32_16x16x4_f32 v[30:33], v13, v243, v[30:33]
	global_load_dword v243, v[220:221], off offset:768
	s_waitcnt vmcnt(17)
	v_mfma_f32_16x16x4_f32 v[30:33], v20, v244, v[30:33]
	global_load_dword v244, v[222:223], off offset:768
	s_waitcnt vmcnt(17)
	v_mfma_f32_16x16x4_f32 v[30:33], v21, v245, v[30:33]
	global_load_dword v245, v[224:225], off offset:768
	s_waitcnt vmcnt(17)
	v_mfma_f32_16x16x4_f32 v[30:33], v24, v246, v[30:33]
	global_load_dword v246, v[226:227], off offset:768
	s_waitcnt vmcnt(17)
	v_mfma_f32_16x16x4_f32 v[30:33], v25, v247, v[30:33]
	global_load_dword v247, v[228:229], off offset:768
	v_mul_f32_e64 v36, v28, |v251|
	s_waitcnt vmcnt(17)
	v_mfma_f32_16x16x4_f32 v[30:33], v22, v248, v[30:33]
	global_load_dword v248, v[230:231], off offset:768
	v_mul_f32_e64 v37, v27, |v251|
	v_mul_f32_e64 v38, v26, |v251|
	v_mul_f32_e64 v29, v0, |v251|
	v_mul_f32_e32 v36, 0x3fb8aa3b, v36
	v_mul_f32_e32 v37, 0x3fb8aa3b, v37
	v_mul_f32_e32 v38, 0x3fb8aa3b, v38
	v_mul_f32_e32 v29, 0x3fb8aa3b, v29
	s_waitcnt vmcnt(17)
	v_mfma_f32_16x16x4_f32 v[30:33], v23, v249, v[30:33]
	global_load_dword v249, v[232:233], off offset:768
	v_exp_f32_e32 v36, v36
	v_exp_f32_e32 v37, v37
	v_exp_f32_e32 v38, v38
	v_exp_f32_e32 v39, v29
	s_nop 5
	v_pk_mul_f32 v[30:31], v[30:31], v[36:37]
	v_pk_mul_f32 v[32:33], v[32:33], v[38:39]
	v_add_f32_e64 v29, |v30|, |v31|
	v_add_f32_e64 v29, |v32|, v29
	v_add_f32_e64 v29, |v33|, v29
	v_add_f32_e32 v53, v53, v29
	global_store_dwordx4 v[34:35], v[30:33], off
	s_cbranch_vccnz .LBB0_123
	s_nop 0
	v_and_b32_e32 v30, 64, v48
	v_xor_b32_e32 v29, 16, v48
	v_add_u32_e32 v30, 64, v30
	v_cmp_lt_i32_e32 vcc, v29, v30
	v_xor_b32_e32 v31, 32, v48
	s_nop 0
	v_cndmask_b32_e32 v29, v48, v29, vcc
	v_lshlrev_b32_e32 v29, 2, v29
	ds_bpermute_b32 v29, v29, v53
	v_cmp_lt_i32_e32 vcc, v31, v30
	s_waitcnt lgkmcnt(0)
	v_add_f32_e32 v29, v53, v29
	v_cndmask_b32_e32 v30, v48, v31, vcc
	v_lshlrev_b32_e32 v30, 2, v30
	ds_bpermute_b32 v30, v30, v29
	s_and_saveexec_b64 s[8:9], s[0:1]
	s_cbranch_execz .LBB0_122
	v_lshl_add_u64 v[32:33], v[2:3], 2, s[6:7]
	s_waitcnt lgkmcnt(0)
	v_add_f32_e32 v29, v29, v30
	global_atomic_add_f32 v[32:33], v29, off offset:704

; __device__ __forceinline__ void filt_item(const Params& p, int lsel, int tile, float* lds, int wave, float (&colsum)[16], bool flush) {
;     ...
;         for (int ct = 0; ct < 16; ++ct) {
;             const int col = wv * 256 + ct * 16 + l15;
;             const float* wp = p.hy_pos_w3 + (size_t)g * 2048 + col;
;             f32x4 acc = (f32x4){0.f, 0.f, 0.f, 0.f};
; #pragma unroll
;             for (int s_ = 0; s_ < 16; ++s_) acc = __builtin_amdgcn_mfma_f32_16x16x4f32(av[s_], wp[(size_t)s_ * 4 * 2048], acc, 0, 0, 0);
;             const float dec = fabsf(p.hy_decay[col]); float asum = 0.f;
; #pragma unroll
;             for (int r = 0; r < 4; ++r) { const float tn = (float)(t0 + 4 * g + r) * inv_lm1; acc[r] *= __expf(-tn * dec); asum += fabsf(acc[r]); }
;             *(f32x4*)(filt + (size_t)col * L + t0 + 4 * g) = acc;
;             colsum[ct] += asum;
;             if (flush) { float tot = colsum[ct]; tot += __shfl_xor(tot, 16); tot += __shfl_xor(tot, 32); if (g == 0) atomicAdd(normsum + col, tot); colsum[ct] = 0.f; }
;         }
.LBB0_123:
	s_waitcnt lgkmcnt(0)
	s_waitcnt vmcnt(17)
	v_mfma_f32_16x16x4_f32 v[30:33], v14, v234, 0
	global_load_dword v234, v[6:7], off offset:832
	global_load_dword v251, v[16:17], off offset:832
	s_waitcnt vmcnt(17)
	v_mfma_f32_16x16x4_f32 v[30:33], v15, v235, v[30:33]
	global_load_dword v235, v[204:205], off offset:832
	s_waitcnt vmcnt(17)
	v_mfma_f32_16x16x4_f32 v[30:33], v18, v236, v[30:33]
	global_load_dword v236, v[206:207], off offset:832
	s_waitcnt vmcnt(17)
	v_mfma_f32_16x16x4_f32 v[30:33], v19, v237, v[30:33]
	global_load_dword v237, v[208:209], off offset:832
	s_waitcnt vmcnt(17)
	v_mfma_f32_16x16x4_f32 v[30:33], v8, v238, v[30:33]
	global_load_dword v238, v[210:211], off offset:832
	s_waitcnt vmcnt(17)
	v_mfma_f32_16x16x4_f32 v[30:33], v9, v239, v[30:33]
	global_load_dword v239, v[212:213], off offset:832
	s_waitcnt vmcnt(17)
	v_mfma_f32_16x16x4_f32 v[30:33], v10, v240, v[30:33]
	global_load_dword v240, v[214:215], off offset:832
	s_waitcnt vmcnt(17)
	v_mfma_f32_16x16x4_f32 v[30:33], v11, v241, v[30:33]
	global_load_dword v241, v[216:217], off offset:832
	s_waitcnt vmcnt(17)
	v_mfma_f32_16x16x4_f32 v[30:33], v12, v242, v[30:33]
	global_load_dword v242, v[218:219], off offset:832
	v_or_b32_e32 v34, 0xc0, v2
	v_ashrrev_i32_e32 v35, 31, v34
	v_lshlrev_b64 v[34:35], s24, v[34:35]
	v_lshl_add_u64 v[34:35], v[34:35], 2, v[4:5]
	s_and_b64 vcc, exec, s[4:5]
	s_waitcnt vmcnt(17)
	v_mfma_f32_16x16x4_f32 v[30:33], v13, v243, v[30:33]
	global_load_dword v243, v[220:221], off offset:832
	s_waitcnt vmcnt(17)
	v_mfma_f32_16x16x4_f32 v[30:33], v20, v244, v[30:33]
	global_load_dword v244, v[222:223], off offset:832
	s_waitcnt vmcnt(17)
	v_mfma_f32_16x16x4_f32 v[30:33], v21, v245, v[30:33]
	global_load_dword v245, v[224:225], off offset:832
	s_waitcnt vmcnt(17)
	v_mfma_f32_16x16x4_f32 v[30:33], v24, v246, v[30:33]
	global_load_dword v246, v[226:227], off offset:832
	s_waitcnt vmcnt(17)
	v_mfma_f32_16x16x4_f32 v[30:33], v25, v247, v[30:33]
	global_load_dword v247, v[228:229], off offset:832
	v_mul_f32_e64 v36, v28, |v250|
	s_waitcnt vmcnt(17)
	v_mfma_f32_16x16x4_f32 v[30:33], v22, v248, v[30:33]
	global_load_dword v248, v[230:231], off offset:832
	v_mul_f32_e64 v37, v27, |v250|
	v_mul_f32_e64 v38, v26, |v250|
	v_mul_f32_e64 v29, v0, |v250|
	v_mul_f32_e32 v36, 0x3fb8aa3b, v36
	v_mul_f32_e32 v37, 0x3fb8aa3b, v37
	v_mul_f32_e32 v38, 0x3fb8aa3b, v38
	v_mul_f32_e32 v29, 0x3fb8aa3b, v29
	s_waitcnt vmcnt(17)
	v_mfma_f32_16x16x4_f32 v[30:33], v23, v249, v[30:33]
	global_load_dword v249, v[232:233], off offset:832
	v_exp_f32_e32 v36, v36
	v_exp_f32_e32 v37, v37
	v_exp_f32_e32 v38, v38
	v_exp_f32_e32 v39, v29
	s_nop 5
	v_pk_mul_f32 v[30:31], v[30:31], v[36:37]
	v_pk_mul_f32 v[32:33], v[32:33], v[38:39]
	v_add_f32_e64 v29, |v30|, |v31|
	v_add_f32_e64 v29, |v32|, v29
	v_add_f32_e64 v29, |v33|, v29
	v_add_f32_e32 v52, v52, v29
	global_store_dwordx4 v[34:35], v[30:33], off
	s_cbranch_vccnz .LBB0_127
	s_nop 0
	v_and_b32_e32 v30, 64, v48
	v_xor_b32_e32 v29, 16, v48
	v_add_u32_e32 v30, 64, v30
	v_cmp_lt_i32_e32 vcc, v29, v30
	v_xor_b32_e32 v31, 32, v48
	s_nop 0
	v_cndmask_b32_e32 v29, v48, v29, vcc
	v_lshlrev_b32_e32 v29, 2, v29
	ds_bpermute_b32 v29, v29, v52
	v_cmp_lt_i32_e32 vcc, v31, v30
	s_waitcnt lgkmcnt(0)
	v_add_f32_e32 v29, v52, v29
	v_cndmask_b32_e32 v30, v48, v31, vcc
	v_lshlrev_b32_e32 v30, 2, v30
	ds_bpermute_b32 v30, v30, v29
	s_and_saveexec_b64 s[8:9], s[0:1]
	s_cbranch_execz .LBB0_126
	v_lshl_add_u64 v[32:33], v[2:3], 2, s[6:7]
	s_waitcnt lgkmcnt(0)
	v_add_f32_e32 v29, v29, v30
	global_atomic_add_f32 v[32:33], v29, off offset:768

; __device__ __forceinline__ void filt_item(const Params& p, int lsel, int tile, float* lds, int wave, float (&colsum)[16], bool flush) {
;     ...
;         for (int ct = 0; ct < 16; ++ct) {
;             const int col = wv * 256 + ct * 16 + l15;
;             const float* wp = p.hy_pos_w3 + (size_t)g * 2048 + col;
;             f32x4 acc = (f32x4){0.f, 0.f, 0.f, 0.f};
; #pragma unroll
;             for (int s_ = 0; s_ < 16; ++s_) acc = __builtin_amdgcn_mfma_f32_16x16x4f32(av[s_], wp[(size_t)s_ * 4 * 2048], acc, 0, 0, 0);
;             const float dec = fabsf(p.hy_decay[col]); float asum = 0.f;
; #pragma unroll
;             for (int r = 0; r < 4; ++r) { const float tn = (float)(t0 + 4 * g + r) * inv_lm1; acc[r] *= __expf(-tn * dec); asum += fabsf(acc[r]); }
;             *(f32x4*)(filt + (size_t)col * L + t0 + 4 * g) = acc;
;             colsum[ct] += asum;
;             if (flush) { float tot = colsum[ct]; tot += __shfl_xor(tot, 16); tot += __shfl_xor(tot, 32); if (g == 0) atomicAdd(normsum + col, tot); colsum[ct] = 0.f; }
;         }
.LBB0_127:
	s_waitcnt lgkmcnt(0)
	s_waitcnt vmcnt(17)
	v_mfma_f32_16x16x4_f32 v[30:33], v14, v234, 0
	global_load_dword v234, v[6:7], off offset:896
	global_load_dword v250, v[16:17], off offset:896
	s_waitcnt vmcnt(17)
	v_mfma_f32_16x16x4_f32 v[30:33], v15, v235, v[30:33]
	global_load_dword v235, v[204:205], off offset:896
	s_waitcnt vmcnt(17)
	v_mfma_f32_16x16x4_f32 v[30:33], v18, v236, v[30:33]
	global_load_dword v236, v[206:207], off offset:896
	s_waitcnt vmcnt(17)
	v_mfma_f32_16x16x4_f32 v[30:33], v19, v237, v[30:33]
	global_load_dword v237, v[208:209], off offset:896
	s_waitcnt vmcnt(17)
	v_mfma_f32_16x16x4_f32 v[30:33], v8, v238, v[30:33]
	global_load_dword v238, v[210:211], off offset:896
	s_waitcnt vmcnt(17)
	v_mfma_f32_16x16x4_f32 v[30:33], v9, v239, v[30:33]
	global_load_dword v239, v[212:213], off offset:896
	s_waitcnt vmcnt(17)
	v_mfma_f32_16x16x4_f32 v[30:33], v10, v240, v[30:33]
	global_load_dword v240, v[214:215], off offset:896
	s_waitcnt vmcnt(17)
	v_mfma_f32_16x16x4_f32 v[30:33], v11, v241, v[30:33]
	global_load_dword v241, v[216:217], off offset:896
	s_waitcnt vmcnt(17)
	v_mfma_f32_16x16x4_f32 v[30:33], v12, v242, v[30:33]
	global_load_dword v242, v[218:219], off offset:896
	v_or_b32_e32 v34, 0xd0, v2
	v_ashrrev_i32_e32 v35, 31, v34
	v_lshlrev_b64 v[34:35], s24, v[34:35]
	v_lshl_add_u64 v[34:35], v[34:35], 2, v[4:5]
	s_and_b64 vcc, exec, s[4:5]
	s_waitcnt vmcnt(17)
	v_mfma_f32_16x16x4_f32 v[30:33], v13, v243, v[30:33]
	global_load_dword v243, v[220:221], off offset:896
	s_waitcnt vmcnt(17)
	v_mfma_f32_16x16x4_f32 v[30:33], v20, v244, v[30:33]
	global_load_dword v244, v[222:223], off offset:896
	s_waitcnt vmcnt(17)
	v_mfma_f32_16x16x4_f32 v[30:33], v21, v245, v[30:33]
	global_load_dword v245, v[224:225], off offset:896
	s_waitcnt vmcnt(17)
	v_mfma_f32_16x16x4_f32 v[30:33], v24, v246, v[30:33]
	global_load_dword v246, v[226:227], off offset:896
	s_waitcnt vmcnt(17)
	v_mfma_f32_16x16x4_f32 v[30:33], v25, v247, v[30:33]
	global_load_dword v247, v[228:229], off offset:896
	v_mul_f32_e64 v36, v28, |v251|
	s_waitcnt vmcnt(17)
	v_mfma_f32_16x16x4_f32 v[30:33], v22, v248, v[30:33]
	global_load_dword v248, v[230:231], off offset:896
	v_mul_f32_e64 v37, v27, |v251|
	v_mul_f32_e64 v38, v26, |v251|
	v_mul_f32_e64 v29, v0, |v251|
	v_mul_f32_e32 v36, 0x3fb8aa3b, v36
	v_mul_f32_e32 v37, 0x3fb8aa3b, v37
	v_mul_f32_e32 v38, 0x3fb8aa3b, v38
	v_mul_f32_e32 v29, 0x3fb8aa3b, v29
	s_waitcnt vmcnt(17)
	v_mfma_f32_16x16x4_f32 v[30:33], v23, v249, v[30:33]
	global_load_dword v249, v[232:233], off offset:896
	v_exp_f32_e32 v36, v36
	v_exp_f32_e32 v37, v37
	v_exp_f32_e32 v38, v38
	v_exp_f32_e32 v39, v29
	s_nop 5
	v_pk_mul_f32 v[30:31], v[30:31], v[36:37]
	v_pk_mul_f32 v[32:33], v[32:33], v[38:39]
	v_add_f32_e64 v29, |v30|, |v31|
	v_add_f32_e64 v29, |v32|, v29
	v_add_f32_e64 v29, |v33|, v29
	v_add_f32_e32 v51, v51, v29
	global_store_dwordx4 v[34:35], v[30:33], off
	s_cbranch_vccnz .LBB0_131
	s_nop 0
	v_and_b32_e32 v30, 64, v48
	v_xor_b32_e32 v29, 16, v48
	v_add_u32_e32 v30, 64, v30
	v_cmp_lt_i32_e32 vcc, v29, v30
	v_xor_b32_e32 v31, 32, v48
	s_nop 0
	v_cndmask_b32_e32 v29, v48, v29, vcc
	v_lshlrev_b32_e32 v29, 2, v29
	ds_bpermute_b32 v29, v29, v51
	v_cmp_lt_i32_e32 vcc, v31, v30
	s_waitcnt lgkmcnt(0)
	v_add_f32_e32 v29, v51, v29
	v_cndmask_b32_e32 v30, v48, v31, vcc
	v_lshlrev_b32_e32 v30, 2, v30
	ds_bpermute_b32 v30, v30, v29
	s_and_saveexec_b64 s[8:9], s[0:1]
	s_cbranch_execz .LBB0_130
	v_lshl_add_u64 v[32:33], v[2:3], 2, s[6:7]
	s_waitcnt lgkmcnt(0)
	v_add_f32_e32 v29, v29, v30
	global_atomic_add_f32 v[32:33], v29, off offset:832

; __device__ __forceinline__ void filt_item(const Params& p, int lsel, int tile, float* lds, int wave, float (&colsum)[16], bool flush) {
;     ...
;         for (int ct = 0; ct < 16; ++ct) {
;             const int col = wv * 256 + ct * 16 + l15;
;             const float* wp = p.hy_pos_w3 + (size_t)g * 2048 + col;
;             f32x4 acc = (f32x4){0.f, 0.f, 0.f, 0.f};
; #pragma unroll
;             for (int s_ = 0; s_ < 16; ++s_) acc = __builtin_amdgcn_mfma_f32_16x16x4f32(av[s_], wp[(size_t)s_ * 4 * 2048], acc, 0, 0, 0);
;             const float dec = fabsf(p.hy_decay[col]); float asum = 0.f;
; #pragma unroll
;             for (int r = 0; r < 4; ++r) { const float tn = (float)(t0 + 4 * g + r) * inv_lm1; acc[r] *= __expf(-tn * dec); asum += fabsf(acc[r]); }
;             *(f32x4*)(filt + (size_t)col * L + t0 + 4 * g) = acc;
;             colsum[ct] += asum;
;             if (flush) { float tot = colsum[ct]; tot += __shfl_xor(tot, 16); tot += __shfl_xor(tot, 32); if (g == 0) atomicAdd(normsum + col, tot); colsum[ct] = 0.f; }
;         }
.LBB0_131:
	s_waitcnt lgkmcnt(0)
	s_waitcnt vmcnt(17)
	v_mfma_f32_16x16x4_f32 v[30:33], v14, v234, 0
	global_load_dword v234, v[6:7], off offset:960
	global_load_dword v251, v[16:17], off offset:960
	s_waitcnt vmcnt(17)
	v_mfma_f32_16x16x4_f32 v[30:33], v15, v235, v[30:33]
	global_load_dword v235, v[204:205], off offset:960
	s_waitcnt vmcnt(17)
	v_mfma_f32_16x16x4_f32 v[30:33], v18, v236, v[30:33]
	global_load_dword v236, v[206:207], off offset:960
	s_waitcnt vmcnt(17)
	v_mfma_f32_16x16x4_f32 v[30:33], v19, v237, v[30:33]
	global_load_dword v237, v[208:209], off offset:960
	s_waitcnt vmcnt(17)
	v_mfma_f32_16x16x4_f32 v[30:33], v8, v238, v[30:33]
	global_load_dword v238, v[210:211], off offset:960
	s_waitcnt vmcnt(17)
	v_mfma_f32_16x16x4_f32 v[30:33], v9, v239, v[30:33]
	global_load_dword v239, v[212:213], off offset:960
	s_waitcnt vmcnt(17)
	v_mfma_f32_16x16x4_f32 v[30:33], v10, v240, v[30:33]
	global_load_dword v240, v[214:215], off offset:960
	s_waitcnt vmcnt(17)
	v_mfma_f32_16x16x4_f32 v[30:33], v11, v241, v[30:33]
	global_load_dword v241, v[216:217], off offset:960
	s_waitcnt vmcnt(17)
	v_mfma_f32_16x16x4_f32 v[30:33], v12, v242, v[30:33]
	global_load_dword v242, v[218:219], off offset:960
	v_or_b32_e32 v34, 0xe0, v2
	v_ashrrev_i32_e32 v35, 31, v34
	v_lshlrev_b64 v[34:35], s24, v[34:35]
	v_lshl_add_u64 v[34:35], v[34:35], 2, v[4:5]
	s_and_b64 vcc, exec, s[4:5]
	s_waitcnt vmcnt(17)
	v_mfma_f32_16x16x4_f32 v[30:33], v13, v243, v[30:33]
	global_load_dword v243, v[220:221], off offset:960
	s_waitcnt vmcnt(17)
	v_mfma_f32_16x16x4_f32 v[30:33], v20, v244, v[30:33]
	global_load_dword v244, v[222:223], off offset:960
	s_waitcnt vmcnt(17)
	v_mfma_f32_16x16x4_f32 v[30:33], v21, v245, v[30:33]
	global_load_dword v245, v[224:225], off offset:960
	s_waitcnt vmcnt(17)
	v_mfma_f32_16x16x4_f32 v[30:33], v24, v246, v[30:33]
	global_load_dword v246, v[226:227], off offset:960
	s_waitcnt vmcnt(17)
	v_mfma_f32_16x16x4_f32 v[30:33], v25, v247, v[30:33]
	global_load_dword v247, v[228:229], off offset:960
	v_mul_f32_e64 v36, v28, |v250|
	s_waitcnt vmcnt(17)
	v_mfma_f32_16x16x4_f32 v[30:33], v22, v248, v[30:33]
	global_load_dword v248, v[230:231], off offset:960
	v_mul_f32_e64 v37, v27, |v250|
	v_mul_f32_e64 v38, v26, |v250|
	v_mul_f32_e64 v29, v0, |v250|
	v_mul_f32_e32 v36, 0x3fb8aa3b, v36
	v_mul_f32_e32 v37, 0x3fb8aa3b, v37
	v_mul_f32_e32 v38, 0x3fb8aa3b, v38
	v_mul_f32_e32 v29, 0x3fb8aa3b, v29
	s_waitcnt vmcnt(17)
	v_mfma_f32_16x16x4_f32 v[30:33], v23, v249, v[30:33]
	global_load_dword v249, v[232:233], off offset:960
	v_exp_f32_e32 v36, v36
	v_exp_f32_e32 v37, v37
	v_exp_f32_e32 v38, v38
	v_exp_f32_e32 v39, v29
	s_nop 5
	v_pk_mul_f32 v[30:31], v[30:31], v[36:37]
	v_pk_mul_f32 v[32:33], v[32:33], v[38:39]
	v_add_f32_e64 v29, |v30|, |v31|
	v_add_f32_e64 v29, |v32|, v29
	v_add_f32_e64 v29, |v33|, v29
	v_add_f32_e32 v50, v50, v29
	global_store_dwordx4 v[34:35], v[30:33], off
	s_cbranch_vccnz .LBB0_135
	s_nop 0
	v_and_b32_e32 v30, 64, v48
	v_xor_b32_e32 v29, 16, v48
	v_add_u32_e32 v30, 64, v30
	v_cmp_lt_i32_e32 vcc, v29, v30
	v_xor_b32_e32 v31, 32, v48
	s_nop 0
	v_cndmask_b32_e32 v29, v48, v29, vcc
	v_lshlrev_b32_e32 v29, 2, v29
	ds_bpermute_b32 v29, v29, v50
	v_cmp_lt_i32_e32 vcc, v31, v30
	s_waitcnt lgkmcnt(0)
	v_add_f32_e32 v29, v50, v29
	v_cndmask_b32_e32 v30, v48, v31, vcc
	v_lshlrev_b32_e32 v30, 2, v30
	ds_bpermute_b32 v30, v30, v29
	s_and_saveexec_b64 s[8:9], s[0:1]
	s_cbranch_execz .LBB0_134
	v_lshl_add_u64 v[32:33], v[2:3], 2, s[6:7]
	s_waitcnt lgkmcnt(0)
	v_add_f32_e32 v29, v29, v30
	global_atomic_add_f32 v[32:33], v29, off offset:896

; __device__ __forceinline__ void filt_item(const Params& p, int lsel, int tile, float* lds, int wave, float (&colsum)[16], bool flush) {
;     ...
;         for (int ct = 0; ct < 16; ++ct) {
;             const int col = wv * 256 + ct * 16 + l15;
;             const float* wp = p.hy_pos_w3 + (size_t)g * 2048 + col;
;             f32x4 acc = (f32x4){0.f, 0.f, 0.f, 0.f};
; #pragma unroll
;             for (int s_ = 0; s_ < 16; ++s_) acc = __builtin_amdgcn_mfma_f32_16x16x4f32(av[s_], wp[(size_t)s_ * 4 * 2048], acc, 0, 0, 0);
;             const float dec = fabsf(p.hy_decay[col]); float asum = 0.f;
; #pragma unroll
;             for (int r = 0; r < 4; ++r) { const float tn = (float)(t0 + 4 * g + r) * inv_lm1; acc[r] *= __expf(-tn * dec); asum += fabsf(acc[r]); }
;             *(f32x4*)(filt + (size_t)col * L + t0 + 4 * g) = acc;
;             colsum[ct] += asum;
;             if (flush) { float tot = colsum[ct]; tot += __shfl_xor(tot, 16); tot += __shfl_xor(tot, 32); if (g == 0) atomicAdd(normsum + col, tot); colsum[ct] = 0.f; }
;         }
.LBB0_135:
	s_waitcnt lgkmcnt(0)
	s_waitcnt vmcnt(17)
	v_mfma_f32_16x16x4_f32 v[30:33], v14, v234, 0
	s_waitcnt vmcnt(15)
	v_mfma_f32_16x16x4_f32 v[30:33], v15, v235, v[30:33]
	s_waitcnt vmcnt(14)
	v_mfma_f32_16x16x4_f32 v[30:33], v18, v236, v[30:33]
	s_waitcnt vmcnt(13)
	v_mfma_f32_16x16x4_f32 v[30:33], v19, v237, v[30:33]
	s_waitcnt vmcnt(12)
	v_mfma_f32_16x16x4_f32 v[30:33], v8, v238, v[30:33]
	s_waitcnt vmcnt(11)
	v_mfma_f32_16x16x4_f32 v[30:33], v9, v239, v[30:33]
	s_waitcnt vmcnt(10)
	v_mfma_f32_16x16x4_f32 v[30:33], v10, v240, v[30:33]
	s_waitcnt vmcnt(9)
	v_mfma_f32_16x16x4_f32 v[8:11], v11, v241, v[30:33]
	s_waitcnt vmcnt(8)
	v_mfma_f32_16x16x4_f32 v[8:11], v12, v242, v[8:11]
	s_nop 0
	s_and_b64 vcc, exec, s[4:5]
	s_waitcnt vmcnt(7)
	v_mfma_f32_16x16x4_f32 v[6:9], v13, v243, v[8:11]
	s_nop 1
	v_or_b32_e32 v10, 0xf0, v2
	v_ashrrev_i32_e32 v11, 31, v10
	v_lshlrev_b64 v[10:11], s24, v[10:11]
	v_lshl_add_u64 v[10:11], v[10:11], 2, v[4:5]
	v_mul_f32_e64 v15, v28, |v251|
	s_waitcnt vmcnt(6)
	v_mfma_f32_16x16x4_f32 v[6:9], v20, v244, v[6:9]
	v_mul_f32_e64 v16, v27, |v251|
	v_mul_f32_e64 v17, v26, |v251|
	v_mul_f32_e64 v0, v0, |v251|
	v_mul_f32_e32 v13, 0x3fb8aa3b, v16
	v_mul_f32_e32 v0, 0x3fb8aa3b, v0
	v_exp_f32_e32 v13, v13
	s_waitcnt vmcnt(5)
	v_mfma_f32_16x16x4_f32 v[6:9], v21, v245, v[6:9]
	s_waitcnt vmcnt(4)
	v_mfma_f32_16x16x4_f32 v[6:9], v24, v246, v[6:9]
	s_waitcnt vmcnt(3)
	v_mfma_f32_16x16x4_f32 v[6:9], v25, v247, v[6:9]
	s_waitcnt vmcnt(2)
	v_mfma_f32_16x16x4_f32 v[6:9], v22, v248, v[6:9]
	v_mul_f32_e32 v12, 0x3fb8aa3b, v15
	v_mul_f32_e32 v15, 0x3fb8aa3b, v17
	v_exp_f32_e32 v12, v12
	s_waitcnt vmcnt(1)
	v_mfma_f32_16x16x4_f32 v[6:9], v23, v249, v[6:9]
	v_exp_f32_e32 v14, v15
	v_exp_f32_e32 v15, v0
	s_nop 7
	v_pk_mul_f32 v[4:5], v[6:7], v[12:13]
	v_pk_mul_f32 v[6:7], v[8:9], v[14:15]
	v_add_f32_e64 v0, |v4|, |v5|
	v_add_f32_e64 v0, |v6|, v0
	v_add_f32_e64 v0, |v7|, v0
	v_add_f32_e32 v49, v49, v0
	global_store_dwordx4 v[10:11], v[4:7], off
	s_cbranch_vccnz .LBB0_16
	s_nop 0
	v_and_b32_e32 v4, 64, v48
	v_xor_b32_e32 v0, 16, v48
	v_add_u32_e32 v4, 64, v4
	v_cmp_lt_i32_e32 vcc, v0, v4
	v_xor_b32_e32 v5, 32, v48
	s_nop 0
	v_cndmask_b32_e32 v0, v48, v0, vcc
	v_lshlrev_b32_e32 v0, 2, v0
	ds_bpermute_b32 v0, v0, v49
	v_cmp_lt_i32_e32 vcc, v5, v4
	s_waitcnt lgkmcnt(0)
	v_add_f32_e32 v0, v49, v0
	v_cndmask_b32_e32 v4, v48, v5, vcc
	v_lshlrev_b32_e32 v4, 2, v4
	ds_bpermute_b32 v4, v4, v0
	s_and_saveexec_b64 s[4:5], s[0:1]
	s_cbranch_execz .LBB0_15
	v_lshl_add_u64 v[2:3], v[2:3], 2, s[6:7]
	s_waitcnt lgkmcnt(0)
	v_add_f32_e32 v0, v0, v4
	global_atomic_add_f32 v[2:3], v0, off offset:960
	s_branch .LBB0_15
